# weight-conversion items: bf16 weight stores write-through sc1 instead of non-temporal (f32 reads stay non-temporal)
# speedup vs baseline: 1.0096x; 1.0096x over previous
; __device__ __forceinline__ void tr_item(const float* __restrict__ W, int ldw, int k0, int n0, bf16* __restrict__ WT, int ldt, int drow, const float* __restrict__ mu, LAS float* scr, int lane, const float* __restrict__ gs = nullptr) {
; #pragma unroll 8
;     for (int i = 0; i < 32; ++i) { const int kk = 2 * i + (lane >> 5); scr[kk * 33 + (lane & 31)] = W[(size_t)(k0 + kk) * ldw + n0 + (lane & 31)]; }
;     asm volatile("s_waitcnt lgkmcnt(0)" ::: "memory");
.LBB0_1426:
	s_lshl_b32 s10, s5, 1
	s_lshl_b32 s11, s8, 1
	v_or_b32_e32 v41, s11, v14
	s_add_i32 s12, s10, 4
	s_add_i32 s13, s11, 4
	s_add_i32 s15, s11, 8
	v_add_u32_e32 v0, s4, v41
	v_or_b32_e32 v42, s12, v15
	v_or_b32_e32 v43, s13, v14
	v_mov_b32_e32 v7, v1
	v_or_b32_e32 v40, s10, v15
	s_add_i32 s17, s11, 12
	v_or_b32_e32 v45, s15, v14
	s_waitcnt lgkmcnt(3)
	v_lshlrev_b64 v[32:33], 12, v[0:1]
	v_add_u32_e32 v6, s7, v42
	v_add_u32_e32 v0, s4, v43
	v_mov_b32_e32 v5, v1
	s_add_i32 s14, s10, 8
	s_add_i32 s16, s10, 12
	s_add_i32 s19, s11, 16
	v_add_u32_e32 v4, s7, v40
	v_or_b32_e32 v47, s17, v14
	v_lshlrev_b64 v[6:7], 12, v[6:7]
	v_lshlrev_b64 v[34:35], 12, v[0:1]
	v_add_u32_e32 v0, s4, v45
	s_add_i32 s21, s11, 20
	v_or_b32_e32 v44, s14, v15
	v_or_b32_e32 v46, s16, v15
	v_or_b32_e32 v49, s19, v14
	v_lshlrev_b64 v[4:5], 12, v[4:5]
	v_lshl_add_u64 v[32:33], v[2:3], 0, v[32:33]
	v_lshl_add_u64 v[6:7], v[2:3], 0, v[6:7]
	v_lshlrev_b64 v[36:37], 12, v[0:1]
	v_add_u32_e32 v0, s4, v47
	v_mov_b32_e32 v9, v1
	v_mov_b32_e32 v11, v1
	s_add_i32 s18, s10, 16
	s_add_i32 s20, s10, 20
	s_add_i32 s23, s11, 24
	v_or_b32_e32 v51, s21, v14
	v_add_u32_e32 v8, s7, v44
	v_add_u32_e32 v10, s7, v46
	v_lshl_add_u64 v[4:5], v[2:3], 0, v[4:5]
	v_lshl_add_u64 v[34:35], v[2:3], 0, v[34:35]
	global_load_dword v56, v[32:33], off nt
	global_load_dword v57, v[4:5], off nt
	global_load_dword v58, v[34:35], off nt
	global_load_dword v59, v[6:7], off nt
	v_lshlrev_b64 v[6:7], 12, v[0:1]
	v_add_u32_e32 v0, s4, v49
	s_add_i32 s22, s10, 24
	s_add_i32 s10, s10, 28
	s_add_i32 s11, s11, 28
	v_or_b32_e32 v48, s18, v15
	v_or_b32_e32 v50, s20, v15
	v_or_b32_e32 v53, s23, v14
	v_lshlrev_b64 v[8:9], 12, v[8:9]
	v_lshlrev_b64 v[10:11], 12, v[10:11]
	v_lshl_add_u64 v[4:5], v[2:3], 0, v[36:37]
	v_lshl_add_u64 v[6:7], v[2:3], 0, v[6:7]
	v_lshlrev_b64 v[32:33], 12, v[0:1]
	v_add_u32_e32 v0, s4, v51
	s_waitcnt lgkmcnt(0)
	v_mov_b32_e32 v13, v1
	v_mov_b32_e32 v27, v1
	v_or_b32_e32 v52, s22, v15
	v_or_b32_e32 v54, s10, v15
	v_or_b32_e32 v55, s11, v14
	v_add_u32_e32 v12, s7, v48
	v_add_u32_e32 v26, s7, v50
	v_lshl_add_u64 v[8:9], v[2:3], 0, v[8:9]
	v_lshl_add_u64 v[10:11], v[2:3], 0, v[10:11]
	global_load_dword v60, v[4:5], off nt
	global_load_dword v61, v[8:9], off nt
	global_load_dword v62, v[6:7], off nt
	global_load_dword v63, v[10:11], off nt
	v_lshlrev_b64 v[6:7], 12, v[0:1]
	v_add_u32_e32 v0, s4, v53
	v_mov_b32_e32 v29, v1
	v_mov_b32_e32 v31, v1
	v_add_u32_e32 v28, s7, v52
	v_add_u32_e32 v30, s7, v54
	v_lshlrev_b64 v[12:13], 12, v[12:13]
	v_lshlrev_b64 v[26:27], 12, v[26:27]
	v_lshl_add_u64 v[4:5], v[2:3], 0, v[32:33]
	v_lshl_add_u64 v[6:7], v[2:3], 0, v[6:7]
	v_lshlrev_b64 v[8:9], 12, v[0:1]
	v_add_u32_e32 v0, s4, v55
	v_lshlrev_b64 v[28:29], 12, v[28:29]
	v_lshlrev_b64 v[30:31], 12, v[30:31]
	v_lshl_add_u64 v[12:13], v[2:3], 0, v[12:13]
	v_lshl_add_u64 v[26:27], v[2:3], 0, v[26:27]
	global_load_dword v64, v[4:5], off nt
	global_load_dword v65, v[12:13], off nt
	global_load_dword v66, v[6:7], off nt
	global_load_dword v67, v[26:27], off nt
	v_lshl_add_u64 v[4:5], v[2:3], 0, v[8:9]
	v_lshlrev_b64 v[6:7], 12, v[0:1]
	v_lshl_add_u64 v[28:29], v[2:3], 0, v[28:29]
	v_lshl_add_u64 v[30:31], v[2:3], 0, v[30:31]
	v_lshl_add_u64 v[6:7], v[2:3], 0, v[6:7]
	global_load_dword v0, v[4:5], off nt
	global_load_dword v68, v[28:29], off nt
	global_load_dword v69, v[6:7], off nt
	global_load_dword v70, v[30:31], off nt
	s_add_i32 s8, s8, 16
	s_add_i32 s5, s5, 16
	s_add_i32 s9, s9, -16
	v_mad_u64_u32 v[4:5], s[10:11], v41, s26, v[18:19]
	s_cmp_lg_u32 s9, 0
	v_mad_u64_u32 v[6:7], s[10:11], v40, s26, v[18:19]
	v_mad_u64_u32 v[8:9], s[10:11], v43, s26, v[18:19]
	v_mad_u64_u32 v[10:11], s[10:11], v42, s26, v[18:19]
	v_mad_u64_u32 v[12:13], s[10:11], v45, s26, v[18:19]
	v_mad_u64_u32 v[26:27], s[10:11], v44, s26, v[18:19]
	v_mad_u64_u32 v[28:29], s[10:11], v47, s26, v[18:19]
	v_mad_u64_u32 v[30:31], s[10:11], v46, s26, v[18:19]
	v_mad_u64_u32 v[32:33], s[10:11], v49, s26, v[18:19]
	v_mad_u64_u32 v[34:35], s[10:11], v48, s26, v[18:19]
	v_mad_u64_u32 v[36:37], s[10:11], v51, s26, v[18:19]
	v_mad_u64_u32 v[40:41], s[10:11], v50, s26, v[18:19]
	v_mad_u64_u32 v[42:43], s[10:11], v53, s26, v[18:19]
	v_mad_u64_u32 v[44:45], s[10:11], v52, s26, v[18:19]
	v_mad_u64_u32 v[46:47], s[10:11], v55, s26, v[18:19]
	v_mad_u64_u32 v[48:49], s[10:11], v54, s26, v[18:19]
	s_waitcnt vmcnt(15)
	ds_write_b32 v4, v56
	s_waitcnt vmcnt(14)
	ds_write_b32 v6, v57
	s_waitcnt vmcnt(13)
	ds_write_b32 v8, v58
	s_waitcnt vmcnt(12)
	ds_write_b32 v10, v59
	s_waitcnt vmcnt(11)
	ds_write_b32 v12, v60
	s_waitcnt vmcnt(10)
	ds_write_b32 v26, v61
	s_waitcnt vmcnt(9)
	ds_write_b32 v28, v62
	s_waitcnt vmcnt(8)
	ds_write_b32 v30, v63
	s_waitcnt vmcnt(7)
	ds_write_b32 v32, v64
	s_waitcnt vmcnt(6)
	ds_write_b32 v34, v65
	s_waitcnt vmcnt(5)
	ds_write_b32 v36, v66
	s_waitcnt vmcnt(4)
	ds_write_b32 v40, v67
	s_waitcnt vmcnt(3)
	ds_write_b32 v42, v0
	s_waitcnt vmcnt(2)
	ds_write_b32 v44, v68
	s_waitcnt vmcnt(1)
	ds_write_b32 v46, v69
	s_waitcnt vmcnt(0)
	ds_write_b32 v48, v70
	s_cbranch_scc1 .LBB0_1426
; #define LAS __attribute__((address_space(3)))
; __device__ __forceinline__ v4u pack8(const float (&f)[8]) { v4u w; w.x = cvt_pk_bf16(f[0], f[1]); w.y = cvt_pk_bf16(f[2], f[3]); w.z = cvt_pk_bf16(f[4], f[5]); w.w = cvt_pk_bf16(f[6], f[7]); return w; }
; __device__ __forceinline__ void tr_item(const float* __restrict__ W, int ldw, int k0, int n0, bf16* __restrict__ WT, int ldt, int drow, const float* __restrict__ mu, LAS float* scr, int lane, const float* __restrict__ gs = nullptr) {
;     ...
;     for (int j = 0; j < 4; ++j) {
;         const int n = (lane >> 3) + 8 * j; const LAS float* s = scr + (8 * c) * 33 + n;
;         float f[8];
; #pragma unroll
;         for (int e = 0; e < 8; ++e) f[e] = s[e * 33];
;         bf16* dp = WT + (size_t)(drow + n) * ldt + k0 + 8 * c;
;         if (mu) {
;             float f1[8], f2[8];
; #pragma unroll
;             for (int e = 0; e < 8; ++e) { f1[e] = f[e] * (1.f - mv[e]); f2[e] = f[e] * mv[e]; }
;             *(v4u*)dp = pack8(f1); *(v4u*)(dp + 1024) = pack8(f2);
;         } else { if (gs) {
; #pragma unroll
;             for (int e = 0; e < 8; ++e) f[e] *= mv[e]; }
;             *(v4u*)dp = pack8(f); }
;     }
; __device__ __forceinline__ void ph_p0(const Params& p, LAS unsigned char* lds, int tid, int lane, int wave) {
;     ...
;         { const int i = r / 1408, q = r % 1408, kb = q / 32, nb = q % 32;
;             tr_item(p.in[I_WD] + (size_t)i * DFF * D, D, 64 * kb, 32 * nb, (bf16*)(ws + WS_WD + i * SZ_WD), DFF, 32 * nb, nullptr, scr, lane); }
	s_mul_i32 s1, s1, 0x580000
	v_readlane_b32 s5, v252, 10
	s_add_u32 s1, s5, s1
	v_readlane_b32 s5, v252, 11
	s_addc_u32 s5, s5, 0
	s_lshl_b32 s4, s4, 1
	s_add_u32 s4, s1, s4
	s_addc_u32 s5, s5, 0
	v_lshlrev_b32_e32 v0, 1, v20
	s_waitcnt lgkmcnt(0)
	v_lshl_add_u64 v[6:7], s[4:5], 0, v[0:1]
	v_or_b32_e32 v0, s0, v17
	v_mul_u32_u24_e32 v0, 0xb00, v0
	ds_read2_b32 v[8:9], v19 offset0:33 offset1:41
	ds_read2_b32 v[10:11], v19 offset1:8
	ds_read2_b32 v[12:13], v19 offset0:66 offset1:74
	ds_read2_b32 v[26:27], v19 offset0:99 offset1:107
	ds_read2_b32 v[28:29], v19 offset0:132 offset1:140
	ds_read2_b32 v[30:31], v19 offset0:165 offset1:173
	ds_read2_b32 v[32:33], v19 offset0:198 offset1:206
	ds_read2_b32 v[34:35], v19 offset0:231 offset1:239
	v_lshlrev_b32_e32 v0, 1, v0
	v_lshl_add_u64 v[36:37], v[6:7], 0, v[0:1]
	v_or_b32_e32 v0, s0, v21
	v_mul_u32_u24_e32 v0, 0xb00, v0
	v_lshlrev_b32_e32 v0, 1, v0
	s_waitcnt lgkmcnt(6)
	v_cvt_pk_bf16_f32 v2, v10, v8
	s_waitcnt lgkmcnt(4)
	v_cvt_pk_bf16_f32 v3, v12, v26
	s_waitcnt lgkmcnt(2)
	v_cvt_pk_bf16_f32 v4, v28, v30
	s_waitcnt lgkmcnt(0)
	v_cvt_pk_bf16_f32 v5, v32, v34
	global_store_dwordx4 v[36:37], v[2:5], off sc1
	v_lshl_add_u64 v[36:37], v[6:7], 0, v[0:1]
	v_or_b32_e32 v0, s0, v38
	v_cvt_pk_bf16_f32 v2, v11, v9
	v_cvt_pk_bf16_f32 v3, v13, v27
	v_cvt_pk_bf16_f32 v4, v29, v31
	v_cvt_pk_bf16_f32 v5, v33, v35
	global_store_dwordx4 v[36:37], v[2:5], off sc1
	v_mul_u32_u24_e32 v0, 0xb00, v0
	ds_read2_b32 v[8:9], v19 offset0:16 offset1:24
	ds_read2_b32 v[10:11], v19 offset0:49 offset1:57
	ds_read2_b32 v[12:13], v19 offset0:82 offset1:90
	ds_read2_b32 v[26:27], v19 offset0:115 offset1:123
	ds_read2_b32 v[28:29], v19 offset0:148 offset1:156
	ds_read2_b32 v[30:31], v19 offset0:181 offset1:189
	ds_read2_b32 v[32:33], v19 offset0:214 offset1:222
	ds_read2_b32 v[34:35], v19 offset0:247 offset1:255
	v_lshlrev_b32_e32 v0, 1, v0
	v_lshl_add_u64 v[36:37], v[6:7], 0, v[0:1]
	v_or_b32_e32 v0, s0, v39
	v_mul_u32_u24_e32 v0, 0xb00, v0
	v_lshlrev_b32_e32 v0, 1, v0
	s_waitcnt lgkmcnt(6)
	v_cvt_pk_bf16_f32 v2, v8, v10
	s_waitcnt lgkmcnt(4)
	v_cvt_pk_bf16_f32 v3, v12, v26
	s_waitcnt lgkmcnt(2)
	v_cvt_pk_bf16_f32 v4, v28, v30
	s_waitcnt lgkmcnt(0)
	v_cvt_pk_bf16_f32 v5, v32, v34
	v_lshl_add_u64 v[6:7], v[6:7], 0, v[0:1]
	global_store_dwordx4 v[36:37], v[2:5], off sc1
	s_mov_b64 s[0:1], 0
	s_nop 0
	v_cvt_pk_bf16_f32 v2, v9, v11
	v_cvt_pk_bf16_f32 v3, v13, v27
	v_cvt_pk_bf16_f32 v4, v29, v31
	v_cvt_pk_bf16_f32 v5, v33, v35
	global_store_dwordx4 v[6:7], v[2:5], off sc1
	s_waitcnt lgkmcnt(0)

; #define LAS __attribute__((address_space(3)))
; __device__ __forceinline__ v4u pack8(const float (&f)[8]) { v4u w; w.x = cvt_pk_bf16(f[0], f[1]); w.y = cvt_pk_bf16(f[2], f[3]); w.z = cvt_pk_bf16(f[4], f[5]); w.w = cvt_pk_bf16(f[6], f[7]); return w; }
; __device__ __forceinline__ void tr_item(const float* __restrict__ W, int ldw, int k0, int n0, bf16* __restrict__ WT, int ldt, int drow, const float* __restrict__ mu, LAS float* scr, int lane, const float* __restrict__ gs = nullptr) {
;     ...
;     } else if (gs) {
; #pragma unroll
;         for (int e = 0; e < 8; ++e) mv[e] = gs[k0 + 8 * c + e];
;     }
; #pragma unroll
;     for (int j = 0; j < 4; ++j) {
;         const int n = (lane >> 3) + 8 * j; const LAS float* s = scr + (8 * c) * 33 + n;
;         float f[8];
; #pragma unroll
;         for (int e = 0; e < 8; ++e) f[e] = s[e * 33];
;         bf16* dp = WT + (size_t)(drow + n) * ldt + k0 + 8 * c;
;         if (mu) {
;             float f1[8], f2[8];
; #pragma unroll
;             for (int e = 0; e < 8; ++e) { f1[e] = f[e] * (1.f - mv[e]); f2[e] = f[e] * mv[e]; }
;             *(v4u*)dp = pack8(f1); *(v4u*)(dp + 1024) = pack8(f2);
;         } else { if (gs) {
; #pragma unroll
;             for (int e = 0; e < 8; ++e) f[e] *= mv[e]; }
;             *(v4u*)dp = pack8(f); }
;     }
; __device__ __forceinline__ void ph_p0(const Params& p, LAS unsigned char* lds, int tid, int lane, int wave) {
;     ...
;         if (r < C_WUG) { const int i = r / 2816, q = r % 2816, kb = q / 176, nb = q % 176, n0 = 32 * nb;
;             const int drow = n0 < DFF ? 256 * (n0 / 128) + (n0 % 128) : 256 * ((n0 - DFF) / 128) + 128 + ((n0 - DFF) % 128);
;             tr_item(p.in[I_WUG] + (size_t)i * D * 2 * DFF, 2 * DFF, 64 * kb, n0, (bf16*)(ws + WS_WUG + i * SZ_WUG), D, drow, nullptr, scr, lane, p.in[I_NFFN] + (size_t)i * D); continue; }
.LBB0_1437:
	s_mul_i32 s0, s0, 0xb00000
	v_readlane_b32 s5, v252, 12
	s_add_u32 s0, s5, s0
	v_readlane_b32 s5, v252, 13
	s_addc_u32 s5, s5, 0
	s_lshl_b32 s1, s1, 1
	ds_read2_b32 v[30:31], v19 offset0:33 offset1:41
	ds_read2_b32 v[32:33], v19 offset0:66 offset1:74
	ds_read2_b32 v[34:35], v19 offset0:99 offset1:107
	ds_read2_b32 v[36:37], v19 offset0:132 offset1:140
	ds_read2_b32 v[40:41], v19 offset0:165 offset1:173
	ds_read2_b32 v[42:43], v19 offset0:198 offset1:206
	ds_read2_b32 v[44:45], v19 offset1:8
	ds_read2_b32 v[46:47], v19 offset0:231 offset1:239
	s_add_u32 s0, s0, s1
	s_addc_u32 s1, s5, 0
	v_lshlrev_b32_e32 v0, 1, v20
	v_lshl_add_u64 v[12:13], s[0:1], 0, v[0:1]
	v_add_u32_e32 v0, s4, v17
	v_lshlrev_b64 v[26:27], 11, v[0:1]
	v_lshl_add_u64 v[48:49], v[12:13], 0, v[26:27]
	s_waitcnt lgkmcnt(1)
	v_mov_b32_e32 v26, v44
	v_mov_b32_e32 v27, v30
	v_mov_b32_e32 v28, v32
	v_mov_b32_e32 v29, v34
	v_mov_b32_e32 v52, v42
	s_waitcnt lgkmcnt(0)
	v_mov_b32_e32 v53, v46
	v_readlane_b32 s0, v253, 10
	s_waitcnt vmcnt(0)
	v_pk_mul_f32 v[26:27], v[26:27], v[6:7]
	v_pk_mul_f32 v[28:29], v[8:9], v[28:29]
	v_mov_b32_e32 v50, v36
	v_mov_b32_e32 v51, v40
	v_pk_mul_f32 v[4:5], v[4:5], v[52:53]
	v_readlane_b32 s1, v253, 11
	v_pk_mul_f32 v[50:51], v[2:3], v[50:51]
	s_nop 0
	v_cndmask_b32_e64 v0, v4, v42, s[0:1]
	v_cndmask_b32_e64 v28, v28, v32, s[0:1]
	v_cndmask_b32_e64 v29, v29, v34, s[0:1]
	v_cndmask_b32_e64 v26, v26, v44, s[0:1]
	v_cndmask_b32_e64 v27, v27, v30, s[0:1]
	v_cndmask_b32_e64 v4, v5, v46, s[0:1]
	v_cndmask_b32_e64 v5, v50, v36, s[0:1]
	v_cndmask_b32_e64 v36, v51, v40, s[0:1]
	v_cvt_pk_bf16_f32 v26, v26, v27
	v_cvt_pk_bf16_f32 v27, v28, v29
	v_cvt_pk_bf16_f32 v28, v5, v36
	v_cvt_pk_bf16_f32 v29, v0, v4
	v_add_u32_e32 v0, s4, v21
	v_mov_b32_e32 v30, v45
	v_mov_b32_e32 v34, v33
	global_store_dwordx4 v[48:49], v[26:29], off sc1
	v_lshlrev_b64 v[4:5], 11, v[0:1]
	v_mov_b32_e32 v40, v37
	v_pk_mul_f32 v[26:27], v[6:7], v[30:31]
	v_pk_mul_f32 v[28:29], v[8:9], v[34:35]
	v_mov_b32_e32 v46, v43
	v_lshl_add_u64 v[4:5], v[12:13], 0, v[4:5]
	v_pk_mul_f32 v[48:49], v[2:3], v[40:41]
	v_pk_mul_f32 v[50:51], v[10:11], v[46:47]
	v_cndmask_b32_e64 v28, v28, v33, s[0:1]
	v_cndmask_b32_e64 v29, v29, v35, s[0:1]
	v_cndmask_b32_e64 v26, v26, v45, s[0:1]
	v_cndmask_b32_e64 v27, v27, v31, s[0:1]
	v_cndmask_b32_e64 v0, v50, v43, s[0:1]
	v_cndmask_b32_e64 v30, v51, v47, s[0:1]
	v_cndmask_b32_e64 v32, v48, v37, s[0:1]
	v_cndmask_b32_e64 v34, v49, v41, s[0:1]
	v_cvt_pk_bf16_f32 v26, v26, v27
	v_cvt_pk_bf16_f32 v27, v28, v29
	v_cvt_pk_bf16_f32 v28, v32, v34
	v_cvt_pk_bf16_f32 v29, v0, v30
	global_store_dwordx4 v[4:5], v[26:29], off sc1
	ds_read2_b32 v[4:5], v19 offset0:16 offset1:24
	ds_read2_b32 v[30:31], v19 offset0:49 offset1:57
	ds_read2_b32 v[32:33], v19 offset0:82 offset1:90
	ds_read2_b32 v[34:35], v19 offset0:115 offset1:123
	ds_read2_b32 v[36:37], v19 offset0:148 offset1:156
	ds_read2_b32 v[40:41], v19 offset0:181 offset1:189
	ds_read2_b32 v[42:43], v19 offset0:214 offset1:222
	ds_read2_b32 v[44:45], v19 offset0:247 offset1:255
	v_add_u32_e32 v0, s4, v38
	v_lshlrev_b64 v[26:27], 11, v[0:1]
	v_lshl_add_u64 v[46:47], v[12:13], 0, v[26:27]
	s_waitcnt lgkmcnt(7)
	v_mov_b32_e32 v26, v4
	s_waitcnt lgkmcnt(6)
	v_mov_b32_e32 v27, v30
	s_waitcnt lgkmcnt(5)
	v_mov_b32_e32 v28, v32
	s_waitcnt lgkmcnt(4)
	v_mov_b32_e32 v29, v34
	s_waitcnt lgkmcnt(3)
	v_mov_b32_e32 v48, v36
	s_waitcnt lgkmcnt(2)
	v_mov_b32_e32 v49, v40
	s_waitcnt lgkmcnt(1)
	v_mov_b32_e32 v50, v42
	s_waitcnt lgkmcnt(0)
	v_mov_b32_e32 v51, v44
	v_pk_mul_f32 v[26:27], v[6:7], v[26:27]
	v_pk_mul_f32 v[28:29], v[8:9], v[28:29]
	v_pk_mul_f32 v[48:49], v[2:3], v[48:49]
	v_pk_mul_f32 v[50:51], v[10:11], v[50:51]
	v_cndmask_b32_e64 v40, v49, v40, s[0:1]
	v_cndmask_b32_e64 v0, v50, v42, s[0:1]
	v_cndmask_b32_e64 v28, v28, v32, s[0:1]
	v_cndmask_b32_e64 v29, v29, v34, s[0:1]
	v_cndmask_b32_e64 v4, v26, v4, s[0:1]
	v_cndmask_b32_e64 v26, v27, v30, s[0:1]
	v_cndmask_b32_e64 v42, v51, v44, s[0:1]
	v_cndmask_b32_e64 v36, v48, v36, s[0:1]
	v_cvt_pk_bf16_f32 v26, v4, v26
	v_cvt_pk_bf16_f32 v27, v28, v29
	v_cvt_pk_bf16_f32 v28, v36, v40
	v_cvt_pk_bf16_f32 v29, v0, v42
	v_add_u32_e32 v0, s4, v39
	v_mov_b32_e32 v30, v5
	v_mov_b32_e32 v34, v33
	v_mov_b32_e32 v40, v37
	v_mov_b32_e32 v44, v43
	global_store_dwordx4 v[46:47], v[26:29], off sc1
	v_pk_mul_f32 v[6:7], v[6:7], v[30:31]
	v_pk_mul_f32 v[8:9], v[8:9], v[34:35]
	v_lshlrev_b64 v[26:27], 11, v[0:1]
	v_pk_mul_f32 v[2:3], v[2:3], v[40:41]
	v_pk_mul_f32 v[10:11], v[10:11], v[44:45]
	v_lshl_add_u64 v[12:13], v[12:13], 0, v[26:27]
	v_cndmask_b32_e64 v0, v10, v43, s[0:1]
	v_cndmask_b32_e64 v10, v11, v45, s[0:1]
	v_cndmask_b32_e64 v4, v2, v37, s[0:1]
	v_cndmask_b32_e64 v11, v3, v41, s[0:1]
	v_cndmask_b32_e64 v3, v8, v33, s[0:1]
	v_cndmask_b32_e64 v2, v6, v5, s[0:1]
	v_cndmask_b32_e64 v5, v7, v31, s[0:1]
	v_cndmask_b32_e64 v8, v9, v35, s[0:1]
	v_cvt_pk_bf16_f32 v2, v2, v5
	v_cvt_pk_bf16_f32 v3, v3, v8
	v_cvt_pk_bf16_f32 v4, v4, v11
	v_cvt_pk_bf16_f32 v5, v0, v10
	global_store_dwordx4 v[12:13], v[2:5], off sc1
	s_waitcnt lgkmcnt(0)
	s_mov_b64 s[0:1], 0

; __device__ __forceinline__ void tr_item(const float* __restrict__ W, int ldw, int k0, int n0, bf16* __restrict__ WT, int ldt, int drow, const float* __restrict__ mu, LAS float* scr, int lane, const float* __restrict__ gs = nullptr) {
; #pragma unroll 8
;     for (int i = 0; i < 32; ++i) { const int kk = 2 * i + (lane >> 5); scr[kk * 33 + (lane & 31)] = W[(size_t)(k0 + kk) * ldw + n0 + (lane & 31)]; }
;     asm volatile("s_waitcnt lgkmcnt(0)" ::: "memory");
.LBB0_1440:
	s_lshl_b32 s9, s4, 1
	s_lshl_b32 s10, s7, 1
	v_or_b32_e32 v41, s10, v14
	s_add_i32 s11, s9, 4
	s_add_i32 s12, s10, 4
	s_add_i32 s14, s10, 8
	v_add_u32_e32 v0, s1, v41
	v_or_b32_e32 v42, s11, v15
	v_or_b32_e32 v43, s12, v14
	v_mov_b32_e32 v7, v1
	v_or_b32_e32 v40, s9, v15
	s_add_i32 s16, s10, 12
	v_or_b32_e32 v45, s14, v14
	s_waitcnt lgkmcnt(3)
	v_lshlrev_b64 v[32:33], 12, v[0:1]
	v_add_u32_e32 v6, s5, v42
	v_add_u32_e32 v0, s1, v43
	v_mov_b32_e32 v5, v1
	s_add_i32 s13, s9, 8
	s_add_i32 s15, s9, 12
	s_add_i32 s18, s10, 16
	v_add_u32_e32 v4, s5, v40
	v_or_b32_e32 v47, s16, v14
	v_lshlrev_b64 v[6:7], 12, v[6:7]
	v_lshlrev_b64 v[34:35], 12, v[0:1]
	v_add_u32_e32 v0, s1, v45
	s_add_i32 s20, s10, 20
	v_or_b32_e32 v44, s13, v15
	v_or_b32_e32 v46, s15, v15
	v_or_b32_e32 v49, s18, v14
	v_lshlrev_b64 v[4:5], 12, v[4:5]
	v_lshl_add_u64 v[32:33], v[2:3], 0, v[32:33]
	v_lshl_add_u64 v[6:7], v[2:3], 0, v[6:7]
	v_lshlrev_b64 v[36:37], 12, v[0:1]
	v_add_u32_e32 v0, s1, v47
	v_mov_b32_e32 v9, v1
	v_mov_b32_e32 v11, v1
	s_add_i32 s17, s9, 16
	s_add_i32 s19, s9, 20
	s_add_i32 s22, s10, 24
	v_or_b32_e32 v51, s20, v14
	v_add_u32_e32 v8, s5, v44
	v_add_u32_e32 v10, s5, v46
	v_lshl_add_u64 v[4:5], v[2:3], 0, v[4:5]
	v_lshl_add_u64 v[34:35], v[2:3], 0, v[34:35]
	global_load_dword v56, v[32:33], off nt
	global_load_dword v57, v[4:5], off nt
	global_load_dword v58, v[34:35], off nt
	global_load_dword v59, v[6:7], off nt
	v_lshlrev_b64 v[6:7], 12, v[0:1]
	v_add_u32_e32 v0, s1, v49
	s_add_i32 s21, s9, 24
	s_add_i32 s9, s9, 28
	s_add_i32 s10, s10, 28
	v_or_b32_e32 v48, s17, v15
	v_or_b32_e32 v50, s19, v15
	v_or_b32_e32 v53, s22, v14
	v_lshlrev_b64 v[8:9], 12, v[8:9]
	v_lshlrev_b64 v[10:11], 12, v[10:11]
	v_lshl_add_u64 v[4:5], v[2:3], 0, v[36:37]
	v_lshl_add_u64 v[6:7], v[2:3], 0, v[6:7]
	v_lshlrev_b64 v[32:33], 12, v[0:1]
	v_add_u32_e32 v0, s1, v51
	s_waitcnt lgkmcnt(0)
	v_mov_b32_e32 v13, v1
	v_mov_b32_e32 v27, v1
	v_or_b32_e32 v52, s21, v15
	v_or_b32_e32 v54, s9, v15
	v_or_b32_e32 v55, s10, v14
	v_add_u32_e32 v12, s5, v48
	v_add_u32_e32 v26, s5, v50
	v_lshl_add_u64 v[8:9], v[2:3], 0, v[8:9]
	v_lshl_add_u64 v[10:11], v[2:3], 0, v[10:11]
	global_load_dword v60, v[4:5], off nt
	global_load_dword v61, v[8:9], off nt
	global_load_dword v62, v[6:7], off nt
	global_load_dword v63, v[10:11], off nt
	v_lshlrev_b64 v[6:7], 12, v[0:1]
	v_add_u32_e32 v0, s1, v53
	v_mov_b32_e32 v29, v1
	v_mov_b32_e32 v31, v1
	v_add_u32_e32 v28, s5, v52
	v_add_u32_e32 v30, s5, v54
	v_lshlrev_b64 v[12:13], 12, v[12:13]
	v_lshlrev_b64 v[26:27], 12, v[26:27]
	v_lshl_add_u64 v[4:5], v[2:3], 0, v[32:33]
	v_lshl_add_u64 v[6:7], v[2:3], 0, v[6:7]
	v_lshlrev_b64 v[8:9], 12, v[0:1]
	v_add_u32_e32 v0, s1, v55
	v_lshlrev_b64 v[28:29], 12, v[28:29]
	v_lshlrev_b64 v[30:31], 12, v[30:31]
	v_lshl_add_u64 v[12:13], v[2:3], 0, v[12:13]
	v_lshl_add_u64 v[26:27], v[2:3], 0, v[26:27]
	global_load_dword v64, v[4:5], off nt
	global_load_dword v65, v[12:13], off nt
	global_load_dword v66, v[6:7], off nt
	global_load_dword v67, v[26:27], off nt
	v_lshl_add_u64 v[4:5], v[2:3], 0, v[8:9]
	v_lshlrev_b64 v[6:7], 12, v[0:1]
	v_lshl_add_u64 v[28:29], v[2:3], 0, v[28:29]
	v_lshl_add_u64 v[30:31], v[2:3], 0, v[30:31]
	v_lshl_add_u64 v[6:7], v[2:3], 0, v[6:7]
	global_load_dword v0, v[4:5], off nt
	global_load_dword v68, v[28:29], off nt
	global_load_dword v69, v[6:7], off nt
	global_load_dword v70, v[30:31], off nt
	s_add_i32 s7, s7, 16
	s_add_i32 s4, s4, 16
	s_add_i32 s8, s8, -16
	v_mad_u64_u32 v[4:5], s[10:11], v41, s26, v[18:19]
	s_cmp_lg_u32 s8, 0
	v_mad_u64_u32 v[6:7], s[10:11], v40, s26, v[18:19]
	v_mad_u64_u32 v[8:9], s[10:11], v43, s26, v[18:19]
	v_mad_u64_u32 v[10:11], s[10:11], v42, s26, v[18:19]
	v_mad_u64_u32 v[12:13], s[10:11], v45, s26, v[18:19]
	v_mad_u64_u32 v[26:27], s[10:11], v44, s26, v[18:19]
	v_mad_u64_u32 v[28:29], s[10:11], v47, s26, v[18:19]
	v_mad_u64_u32 v[30:31], s[10:11], v46, s26, v[18:19]
	v_mad_u64_u32 v[32:33], s[10:11], v49, s26, v[18:19]
	v_mad_u64_u32 v[34:35], s[10:11], v48, s26, v[18:19]
	v_mad_u64_u32 v[36:37], s[10:11], v51, s26, v[18:19]
	v_mad_u64_u32 v[40:41], s[10:11], v50, s26, v[18:19]
	v_mad_u64_u32 v[42:43], s[10:11], v53, s26, v[18:19]
	v_mad_u64_u32 v[44:45], s[10:11], v52, s26, v[18:19]
	v_mad_u64_u32 v[46:47], s[10:11], v55, s26, v[18:19]
	v_mad_u64_u32 v[48:49], s[10:11], v54, s26, v[18:19]
	s_waitcnt vmcnt(15)
	ds_write_b32 v4, v56
	s_waitcnt vmcnt(14)
	ds_write_b32 v6, v57
	s_waitcnt vmcnt(13)
	ds_write_b32 v8, v58
	s_waitcnt vmcnt(12)
	ds_write_b32 v10, v59
	s_waitcnt vmcnt(11)
	ds_write_b32 v12, v60
	s_waitcnt vmcnt(10)
	ds_write_b32 v26, v61
	s_waitcnt vmcnt(9)
	ds_write_b32 v28, v62
	s_waitcnt vmcnt(8)
	ds_write_b32 v30, v63
	s_waitcnt vmcnt(7)
	ds_write_b32 v32, v64
	s_waitcnt vmcnt(6)
	ds_write_b32 v34, v65
	s_waitcnt vmcnt(5)
	ds_write_b32 v36, v66
	s_waitcnt vmcnt(4)
	ds_write_b32 v40, v67
	s_waitcnt vmcnt(3)
	ds_write_b32 v42, v0
	s_waitcnt vmcnt(2)
	ds_write_b32 v44, v68
	s_waitcnt vmcnt(1)
	ds_write_b32 v46, v69
	s_waitcnt vmcnt(0)
	ds_write_b32 v48, v70
	s_cbranch_scc1 .LBB0_1440
; #define LAS __attribute__((address_space(3)))
; __device__ __forceinline__ v4u pack8(const float (&f)[8]) { v4u w; w.x = cvt_pk_bf16(f[0], f[1]); w.y = cvt_pk_bf16(f[2], f[3]); w.z = cvt_pk_bf16(f[4], f[5]); w.w = cvt_pk_bf16(f[6], f[7]); return w; }
; __device__ __forceinline__ void tr_item(const float* __restrict__ W, int ldw, int k0, int n0, bf16* __restrict__ WT, int ldt, int drow, const float* __restrict__ mu, LAS float* scr, int lane, const float* __restrict__ gs = nullptr) {
;     ...
;     for (int j = 0; j < 4; ++j) {
;         const int n = (lane >> 3) + 8 * j; const LAS float* s = scr + (8 * c) * 33 + n;
;         float f[8];
; #pragma unroll
;         for (int e = 0; e < 8; ++e) f[e] = s[e * 33];
;         bf16* dp = WT + (size_t)(drow + n) * ldt + k0 + 8 * c;
;         if (mu) {
;             float f1[8], f2[8];
; #pragma unroll
;             for (int e = 0; e < 8; ++e) { f1[e] = f[e] * (1.f - mv[e]); f2[e] = f[e] * mv[e]; }
;             *(v4u*)dp = pack8(f1); *(v4u*)(dp + 1024) = pack8(f2);
;         } else { if (gs) {
; #pragma unroll
;             for (int e = 0; e < 8; ++e) f[e] *= mv[e]; }
;             *(v4u*)dp = pack8(f); }
;     }
; __device__ __forceinline__ void ph_p0(const Params& p, LAS unsigned char* lds, int tid, int lane, int wave) {
;     ...
;         if (r < C_WO) { const int j = r / 512, q = r % 512, kb = q / 32, nb = q % 32;
;             tr_item(p.in[I_WO] + (size_t)j * D * D, D, 64 * kb, 32 * nb, (bf16*)(ws + WS_WO + j * SZ_WO), D, 32 * nb, nullptr, scr, lane); continue; }
	s_lshl_b64 s[4:5], s[94:95], 21
	v_readlane_b32 s7, v252, 14
	s_add_u32 s4, s7, s4
	v_readlane_b32 s7, v252, 15
	s_addc_u32 s5, s7, s5
	s_lshl_b32 s1, s1, 1
	s_waitcnt lgkmcnt(0)
	s_add_u32 s4, s4, s1
	s_addc_u32 s5, s5, 0
	v_lshlrev_b32_e32 v0, 1, v20
	ds_read2_b32 v[8:9], v19 offset0:33 offset1:41
	ds_read2_b32 v[10:11], v19 offset1:8
	ds_read2_b32 v[12:13], v19 offset0:66 offset1:74
	ds_read2_b32 v[26:27], v19 offset0:99 offset1:107
	ds_read2_b32 v[28:29], v19 offset0:132 offset1:140
	ds_read2_b32 v[30:31], v19 offset0:165 offset1:173
	ds_read2_b32 v[32:33], v19 offset0:198 offset1:206
	ds_read2_b32 v[34:35], v19 offset0:231 offset1:239
	v_lshl_add_u64 v[6:7], s[4:5], 0, v[0:1]
	v_or_b32_e32 v0, s0, v17
	v_lshlrev_b32_e32 v0, 11, v0
	v_lshl_add_u64 v[36:37], v[6:7], 0, v[0:1]
	v_or_b32_e32 v0, s0, v21
	v_lshlrev_b32_e32 v0, 11, v0
	s_waitcnt lgkmcnt(6)
	v_cvt_pk_bf16_f32 v2, v10, v8
	s_waitcnt lgkmcnt(4)
	v_cvt_pk_bf16_f32 v3, v12, v26
	s_waitcnt lgkmcnt(2)
	v_cvt_pk_bf16_f32 v4, v28, v30
	s_waitcnt lgkmcnt(0)
	v_cvt_pk_bf16_f32 v5, v32, v34
	global_store_dwordx4 v[36:37], v[2:5], off sc1
	v_lshl_add_u64 v[36:37], v[6:7], 0, v[0:1]
	v_or_b32_e32 v0, s0, v38
	v_cvt_pk_bf16_f32 v2, v11, v9
	v_cvt_pk_bf16_f32 v3, v13, v27
	v_cvt_pk_bf16_f32 v4, v29, v31
	v_cvt_pk_bf16_f32 v5, v33, v35
	global_store_dwordx4 v[36:37], v[2:5], off sc1
	ds_read2_b32 v[8:9], v19 offset0:16 offset1:24
	ds_read2_b32 v[10:11], v19 offset0:49 offset1:57
	ds_read2_b32 v[12:13], v19 offset0:82 offset1:90
	ds_read2_b32 v[26:27], v19 offset0:115 offset1:123
	ds_read2_b32 v[28:29], v19 offset0:148 offset1:156
	ds_read2_b32 v[30:31], v19 offset0:181 offset1:189
	ds_read2_b32 v[32:33], v19 offset0:214 offset1:222
	ds_read2_b32 v[34:35], v19 offset0:247 offset1:255
	v_lshlrev_b32_e32 v0, 11, v0
	v_lshl_add_u64 v[36:37], v[6:7], 0, v[0:1]
	v_or_b32_e32 v0, s0, v39
	v_lshlrev_b32_e32 v0, 11, v0
	s_waitcnt lgkmcnt(6)
	v_cvt_pk_bf16_f32 v2, v8, v10
	s_waitcnt lgkmcnt(4)
	v_cvt_pk_bf16_f32 v3, v12, v26
	s_waitcnt lgkmcnt(2)
	v_cvt_pk_bf16_f32 v4, v28, v30
	s_waitcnt lgkmcnt(0)
	v_cvt_pk_bf16_f32 v5, v32, v34
	v_lshl_add_u64 v[6:7], v[6:7], 0, v[0:1]
	global_store_dwordx4 v[36:37], v[2:5], off sc1
	s_nop 1
	v_cvt_pk_bf16_f32 v2, v9, v11
	v_cvt_pk_bf16_f32 v3, v13, v27
	v_cvt_pk_bf16_f32 v4, v29, v31
	v_cvt_pk_bf16_f32 v5, v33, v35
	global_store_dwordx4 v[6:7], v[2:5], off sc1
	s_waitcnt lgkmcnt(0)

; __device__ __forceinline__ void tr_item(const float* __restrict__ W, int ldw, int k0, int n0, bf16* __restrict__ WT, int ldt, int drow, const float* __restrict__ mu, LAS float* scr, int lane, const float* __restrict__ gs = nullptr) {
; #pragma unroll 8
;     for (int i = 0; i < 32; ++i) { const int kk = 2 * i + (lane >> 5); scr[kk * 33 + (lane & 31)] = W[(size_t)(k0 + kk) * ldw + n0 + (lane & 31)]; }
;     asm volatile("s_waitcnt lgkmcnt(0)" ::: "memory");
.LBB0_1445:
	s_lshl_b32 s8, s4, 1
	s_lshl_b32 s9, s5, 1
	v_or_b32_e32 v0, s8, v15
	v_or_b32_e32 v48, s9, v14
	s_add_i32 s10, s8, 4
	s_add_i32 s11, s9, 4
	s_add_i32 s12, s8, 8
	s_add_i32 s13, s9, 8
	s_add_i32 s14, s8, 12
	s_add_i32 s15, s9, 12
	s_add_i32 s16, s8, 16
	s_add_i32 s17, s9, 16
	s_add_i32 s18, s8, 20
	s_add_i32 s19, s9, 20
	s_add_i32 s20, s8, 24
	s_add_i32 s21, s9, 24
	s_add_i32 s8, s8, 28
	s_add_i32 s9, s9, 28
	v_add_u32_e32 v4, s0, v48
	v_or_b32_e32 v49, s10, v15
	v_or_b32_e32 v50, s11, v14
	v_or_b32_e32 v51, s12, v15
	v_or_b32_e32 v52, s13, v14
	v_or_b32_e32 v53, s14, v15
	v_or_b32_e32 v54, s15, v14
	v_or_b32_e32 v55, s16, v15
	v_or_b32_e32 v56, s17, v14
	v_or_b32_e32 v57, s18, v15
	v_or_b32_e32 v58, s19, v14
	v_or_b32_e32 v59, s20, v15
	v_or_b32_e32 v60, s21, v14
	v_or_b32_e32 v61, s8, v15
	v_or_b32_e32 v62, s9, v14
	v_add_u32_e32 v2, s1, v0
	v_ashrrev_i32_e32 v5, 31, v4
	v_add_u32_e32 v6, s1, v49
	v_add_u32_e32 v8, s0, v50
	v_add_u32_e32 v10, s1, v51
	s_waitcnt lgkmcnt(0)
	v_add_u32_e32 v12, s0, v52
	v_add_u32_e32 v26, s1, v53
	v_add_u32_e32 v28, s0, v54
	v_add_u32_e32 v30, s1, v55
	v_add_u32_e32 v32, s0, v56
	v_add_u32_e32 v34, s1, v57
	v_add_u32_e32 v36, s0, v58
	v_add_u32_e32 v40, s1, v59
	v_add_u32_e32 v42, s0, v60
	v_add_u32_e32 v44, s1, v61
	v_add_u32_e32 v46, s0, v62
	v_ashrrev_i32_e32 v3, 31, v2
	v_lshlrev_b64 v[4:5], 7, v[4:5]
	v_ashrrev_i32_e32 v9, 31, v8
	v_ashrrev_i32_e32 v7, 31, v6
	v_ashrrev_i32_e32 v13, 31, v12
	v_ashrrev_i32_e32 v11, 31, v10
	v_ashrrev_i32_e32 v29, 31, v28
	v_ashrrev_i32_e32 v27, 31, v26
	v_ashrrev_i32_e32 v33, 31, v32
	v_ashrrev_i32_e32 v31, 31, v30
	v_ashrrev_i32_e32 v37, 31, v36
	v_ashrrev_i32_e32 v35, 31, v34
	v_ashrrev_i32_e32 v43, 31, v42
	v_ashrrev_i32_e32 v41, 31, v40
	v_ashrrev_i32_e32 v47, 31, v46
	v_ashrrev_i32_e32 v45, 31, v44
	v_lshlrev_b64 v[2:3], 7, v[2:3]
	v_lshl_add_u64 v[4:5], v[24:25], 0, v[4:5]
	v_lshlrev_b64 v[6:7], 7, v[6:7]
	v_lshlrev_b64 v[8:9], 7, v[8:9]
	v_lshlrev_b64 v[10:11], 7, v[10:11]
	v_lshlrev_b64 v[12:13], 7, v[12:13]
	v_lshlrev_b64 v[26:27], 7, v[26:27]
	v_lshlrev_b64 v[28:29], 7, v[28:29]
	v_lshlrev_b64 v[30:31], 7, v[30:31]
	v_lshlrev_b64 v[32:33], 7, v[32:33]
	v_lshlrev_b64 v[34:35], 7, v[34:35]
	v_lshlrev_b64 v[36:37], 7, v[36:37]
	v_lshlrev_b64 v[40:41], 7, v[40:41]
	v_lshlrev_b64 v[42:43], 7, v[42:43]
	v_lshlrev_b64 v[44:45], 7, v[44:45]
	v_lshlrev_b64 v[46:47], 7, v[46:47]
	v_lshl_add_u64 v[2:3], v[24:25], 0, v[2:3]
	v_lshl_add_u64 v[8:9], v[24:25], 0, v[8:9]
	v_lshl_add_u64 v[6:7], v[24:25], 0, v[6:7]
	v_lshl_add_u64 v[12:13], v[24:25], 0, v[12:13]
	v_lshl_add_u64 v[10:11], v[24:25], 0, v[10:11]
	v_lshl_add_u64 v[28:29], v[24:25], 0, v[28:29]
	v_lshl_add_u64 v[26:27], v[24:25], 0, v[26:27]
	v_lshl_add_u64 v[32:33], v[24:25], 0, v[32:33]
	v_lshl_add_u64 v[30:31], v[24:25], 0, v[30:31]
	v_lshl_add_u64 v[36:37], v[24:25], 0, v[36:37]
	v_lshl_add_u64 v[34:35], v[24:25], 0, v[34:35]
	v_lshl_add_u64 v[42:43], v[24:25], 0, v[42:43]
	v_lshl_add_u64 v[40:41], v[24:25], 0, v[40:41]
	v_lshl_add_u64 v[46:47], v[24:25], 0, v[46:47]
	v_lshl_add_u64 v[44:45], v[24:25], 0, v[44:45]
	global_load_dword v63, v[4:5], off nt
	global_load_dword v64, v[2:3], off nt
	global_load_dword v65, v[8:9], off nt
	global_load_dword v66, v[6:7], off nt
	global_load_dword v67, v[12:13], off nt
	global_load_dword v68, v[10:11], off nt
	global_load_dword v69, v[28:29], off nt
	global_load_dword v70, v[26:27], off nt
	global_load_dword v71, v[32:33], off nt
	global_load_dword v72, v[30:31], off nt
	global_load_dword v73, v[36:37], off nt
	global_load_dword v74, v[34:35], off nt
	global_load_dword v75, v[42:43], off nt
	global_load_dword v76, v[40:41], off nt
	global_load_dword v77, v[46:47], off nt
	global_load_dword v78, v[44:45], off nt
	s_add_i32 s5, s5, 16
	s_add_i32 s4, s4, 16
	s_add_i32 s7, s7, -16
	v_mad_u64_u32 v[2:3], s[8:9], v48, s26, v[18:19]
	s_cmp_lg_u32 s7, 0
	v_mad_u64_u32 v[4:5], s[8:9], v0, s26, v[18:19]
	v_mad_u64_u32 v[6:7], s[8:9], v50, s26, v[18:19]
	v_mad_u64_u32 v[8:9], s[8:9], v49, s26, v[18:19]
	v_mad_u64_u32 v[10:11], s[8:9], v52, s26, v[18:19]
	v_mad_u64_u32 v[12:13], s[8:9], v51, s26, v[18:19]
	v_mad_u64_u32 v[26:27], s[8:9], v54, s26, v[18:19]
	v_mad_u64_u32 v[28:29], s[8:9], v53, s26, v[18:19]
	v_mad_u64_u32 v[30:31], s[8:9], v56, s26, v[18:19]
	v_mad_u64_u32 v[32:33], s[8:9], v55, s26, v[18:19]
	v_mad_u64_u32 v[34:35], s[8:9], v58, s26, v[18:19]
	v_mad_u64_u32 v[36:37], s[8:9], v57, s26, v[18:19]
	v_mad_u64_u32 v[40:41], s[8:9], v60, s26, v[18:19]
	v_mad_u64_u32 v[42:43], s[8:9], v59, s26, v[18:19]
	v_mad_u64_u32 v[44:45], s[8:9], v62, s26, v[18:19]
	v_mad_u64_u32 v[46:47], s[8:9], v61, s26, v[18:19]
	s_waitcnt vmcnt(15)
	ds_write_b32 v2, v63
	s_waitcnt vmcnt(14)
	ds_write_b32 v4, v64
	s_waitcnt vmcnt(13)
	ds_write_b32 v6, v65
	s_waitcnt vmcnt(12)
	ds_write_b32 v8, v66
	s_waitcnt vmcnt(11)
	ds_write_b32 v10, v67
	s_waitcnt vmcnt(10)
	ds_write_b32 v12, v68
	s_waitcnt vmcnt(9)
	ds_write_b32 v26, v69
	s_waitcnt vmcnt(8)
	ds_write_b32 v28, v70
	s_waitcnt vmcnt(7)
	ds_write_b32 v30, v71
	s_waitcnt vmcnt(6)
	ds_write_b32 v32, v72
	s_waitcnt vmcnt(5)
	ds_write_b32 v34, v73
	s_waitcnt vmcnt(4)
	ds_write_b32 v36, v74
	s_waitcnt vmcnt(3)
	ds_write_b32 v40, v75
	s_waitcnt vmcnt(2)
	ds_write_b32 v42, v76
	s_waitcnt vmcnt(1)
	ds_write_b32 v44, v77
	s_waitcnt vmcnt(0)
	ds_write_b32 v46, v78
	s_cbranch_scc1 .LBB0_1445
; #define LAS __attribute__((address_space(3)))
; __device__ __forceinline__ v4u pack8(const float (&f)[8]) { v4u w; w.x = cvt_pk_bf16(f[0], f[1]); w.y = cvt_pk_bf16(f[2], f[3]); w.z = cvt_pk_bf16(f[4], f[5]); w.w = cvt_pk_bf16(f[6], f[7]); return w; }
; __device__ __forceinline__ void tr_item(const float* __restrict__ W, int ldw, int k0, int n0, bf16* __restrict__ WT, int ldt, int drow, const float* __restrict__ mu, LAS float* scr, int lane, const float* __restrict__ gs = nullptr) {
;     ...
;     if (mu) {
; #pragma unroll
;         for (int e = 0; e < 8; ++e) mv[e] = mu[k0 + 8 * c + e];
;     } else if (gs) {
; #pragma unroll
;         for (int e = 0; e < 8; ++e) mv[e] = gs[k0 + 8 * c + e];
;     }
; #pragma unroll
;     for (int j = 0; j < 4; ++j) {
;         const int n = (lane >> 3) + 8 * j; const LAS float* s = scr + (8 * c) * 33 + n;
;         float f[8];
; #pragma unroll
;         for (int e = 0; e < 8; ++e) f[e] = s[e * 33];
;         bf16* dp = WT + (size_t)(drow + n) * ldt + k0 + 8 * c;
;         if (mu) {
;             float f1[8], f2[8];
; #pragma unroll
;             for (int e = 0; e < 8; ++e) { f1[e] = f[e] * (1.f - mv[e]); f2[e] = f[e] * mv[e]; }
;             *(v4u*)dp = pack8(f1); *(v4u*)(dp + 1024) = pack8(f2);
;         } else { if (gs) {
; #pragma unroll
;             for (int e = 0; e < 8; ++e) f[e] *= mv[e]; }
;             *(v4u*)dp = pack8(f); }
;     }
; __device__ __forceinline__ void ph_p0(const Params& p, LAS unsigned char* lds, int tid, int lane, int wave) {
;     ...
;         if (r < C_V1) { const int kb = r;
;             tr_item(p.in[I_V1], LV, 64 * kb, 0, (bf16*)(ws + WS_WRW + 1 * SZ_WRW), KRW, 3360, p.in[I_MU] + (size_t)(1 * 6 + 3) * D, scr, lane); continue; }
	v_readlane_b32 s4, v253, 14
	v_or_b32_e32 v0, s0, v20
	v_readlane_b32 s5, v253, 15
	s_waitcnt lgkmcnt(0)
	s_mov_b32 s1, s95
	v_lshl_add_u64 v[6:7], s[0:1], 1, v[22:23]
	v_lshl_add_u64 v[2:3], v[0:1], 2, s[4:5]
	global_load_dwordx4 v[8:11], v[2:3], off
	s_nop 0
	global_load_dwordx4 v[2:5], v[2:3], off offset:16
	ds_read2_b32 v[12:13], v19 offset0:33 offset1:41
	ds_read2_b32 v[30:31], v19 offset0:66 offset1:74
	ds_read2_b32 v[32:33], v19 offset0:99 offset1:107
	ds_read2_b32 v[34:35], v19 offset0:132 offset1:140
	ds_read2_b32 v[36:37], v19 offset0:165 offset1:173
	ds_read2_b32 v[40:41], v19 offset0:198 offset1:206
	ds_read2_b32 v[42:43], v19 offset0:231 offset1:239
	s_mov_b32 s0, 0xd20000
	ds_read2_b32 v[44:45], v19 offset1:8
	ds_read2_b32 v[46:47], v19 offset0:16 offset1:24
	ds_read2_b32 v[48:49], v19 offset0:49 offset1:57
	ds_read2_b32 v[50:51], v19 offset0:82 offset1:90
	v_add_co_u32_e32 v52, vcc, s0, v6
	s_mov_b32 s0, 0xd28000
	s_nop 0
	v_addc_co_u32_e32 v53, vcc, 0, v7, vcc
	v_add_co_u32_e32 v54, vcc, s0, v6
	s_mov_b32 s0, 0xd30000
	s_nop 0
	v_addc_co_u32_e32 v55, vcc, 0, v7, vcc
	s_waitcnt vmcnt(1) lgkmcnt(3)
	v_mul_f32_e32 v26, v8, v44
	v_mul_f32_e32 v27, v9, v12
	v_sub_f32_e32 v57, 1.0, v10
	v_mul_f32_e32 v28, v10, v30
	v_sub_f32_e32 v58, 1.0, v11
	v_mul_f32_e32 v29, v11, v32
	s_waitcnt vmcnt(0)
	v_mul_f32_e32 v60, v2, v34
	v_sub_f32_e32 v61, 1.0, v3
	v_mul_f32_e32 v62, v3, v36
	v_sub_f32_e32 v0, 1.0, v8
	v_sub_f32_e32 v56, 1.0, v9
	v_sub_f32_e32 v59, 1.0, v2
	v_sub_f32_e32 v63, 1.0, v4
	v_mul_f32_e32 v64, v4, v40
	v_sub_f32_e32 v65, 1.0, v5
	v_mul_f32_e32 v66, v5, v42
	v_mul_f32_e32 v67, v8, v45
	v_mul_f32_e32 v68, v9, v13
	v_mul_f32_e32 v69, v10, v31
	v_mul_f32_e32 v70, v11, v33
	v_mul_f32_e32 v71, v2, v35
	v_mul_f32_e32 v72, v3, v37
	v_mul_f32_e32 v73, v4, v41
	v_mul_f32_e32 v74, v5, v43
	v_mul_f32_e32 v75, v57, v30
	v_mul_f32_e32 v76, v58, v32
	v_mul_f32_e32 v36, v61, v36
	v_cvt_pk_bf16_f32 v26, v26, v27
	v_cvt_pk_bf16_f32 v27, v28, v29
	v_cvt_pk_bf16_f32 v28, v60, v62
	v_cvt_pk_bf16_f32 v29, v64, v66
	v_mul_f32_e32 v60, v57, v31
	v_mul_f32_e32 v62, v58, v33
	v_cvt_pk_bf16_f32 v30, v67, v68
	v_cvt_pk_bf16_f32 v31, v69, v70
	v_cvt_pk_bf16_f32 v32, v71, v72
	v_cvt_pk_bf16_f32 v33, v73, v74
	v_mul_f32_e32 v44, v0, v44
	v_mul_f32_e32 v12, v56, v12
	v_mul_f32_e32 v77, v59, v34
	v_mul_f32_e32 v40, v63, v40
	v_mul_f32_e32 v42, v65, v42
	v_mul_f32_e32 v45, v0, v45
	v_mul_f32_e32 v13, v56, v13
	v_mul_f32_e32 v64, v59, v35
	v_mul_f32_e32 v66, v61, v37
	v_mul_f32_e32 v41, v63, v41
	v_mul_f32_e32 v43, v65, v43
	v_cvt_pk_bf16_f32 v34, v44, v12
	v_cvt_pk_bf16_f32 v35, v75, v76
	v_cvt_pk_bf16_f32 v36, v77, v36
	v_cvt_pk_bf16_f32 v37, v40, v42
	global_store_dwordx4 v[52:53], v[26:29], off offset:2048 sc1
	s_waitcnt lgkmcnt(2)
	v_mul_f32_e32 v42, v8, v46
	s_waitcnt lgkmcnt(0)
	v_mul_f32_e32 v44, v10, v50
	v_cvt_pk_bf16_f32 v26, v45, v13
	v_cvt_pk_bf16_f32 v27, v60, v62
	v_cvt_pk_bf16_f32 v28, v64, v66
	v_cvt_pk_bf16_f32 v29, v41, v43
	global_store_dwordx4 v[54:55], v[30:33], off offset:2048 sc1
	global_store_dwordx4 v[52:53], v[34:37], off sc1
	global_store_dwordx4 v[54:55], v[26:29], off sc1
	ds_read2_b32 v[12:13], v19 offset0:115 offset1:123
	ds_read2_b32 v[30:31], v19 offset0:148 offset1:156
	ds_read2_b32 v[32:33], v19 offset0:181 offset1:189
	ds_read2_b32 v[34:35], v19 offset0:214 offset1:222
	ds_read2_b32 v[36:37], v19 offset0:247 offset1:255
	v_mul_f32_e32 v26, v0, v46
	v_mul_f32_e32 v27, v56, v48
	v_mul_f32_e32 v28, v57, v50
	s_waitcnt lgkmcnt(3)
	v_mul_f32_e32 v40, v59, v30
	v_mul_f32_e32 v29, v58, v12
	s_waitcnt lgkmcnt(2)
	v_mul_f32_e32 v41, v61, v32
	v_cvt_pk_bf16_f32 v26, v26, v27
	v_cvt_pk_bf16_f32 v27, v28, v29
	v_cvt_pk_bf16_f32 v28, v40, v41
	v_add_co_u32_e32 v40, vcc, s0, v6
	s_waitcnt lgkmcnt(1)
	v_mul_f32_e32 v45, v63, v34
	s_waitcnt lgkmcnt(0)
	v_mul_f32_e32 v46, v65, v36
	v_cvt_pk_bf16_f32 v29, v45, v46
	v_addc_co_u32_e32 v41, vcc, 0, v7, vcc
	v_mul_f32_e32 v43, v9, v48
	v_mul_f32_e32 v12, v11, v12
	v_mul_f32_e32 v30, v2, v30
	v_mul_f32_e32 v32, v3, v32
	v_mul_f32_e32 v34, v4, v34
	v_mul_f32_e32 v36, v5, v36
	global_store_dwordx4 v[40:41], v[26:29], off sc1
	v_add_co_u32_e32 v6, vcc, 0xd38000, v6
	s_nop 0
	v_cvt_pk_bf16_f32 v26, v42, v43
	v_cvt_pk_bf16_f32 v27, v44, v12
	v_cvt_pk_bf16_f32 v28, v30, v32
	v_cvt_pk_bf16_f32 v29, v34, v36
	global_store_dwordx4 v[40:41], v[26:29], off offset:2048 sc1
	v_mul_f32_e32 v0, v0, v47
	v_mul_f32_e32 v12, v56, v49
	v_mul_f32_e32 v26, v57, v51
	v_mul_f32_e32 v27, v58, v13
	v_mul_f32_e32 v11, v11, v13
	v_mul_f32_e32 v13, v59, v31
	v_mul_f32_e32 v28, v2, v31
	v_mul_f32_e32 v29, v61, v33
	v_mul_f32_e32 v30, v3, v33
	v_mul_f32_e32 v31, v63, v35
	v_mul_f32_e32 v32, v4, v35
	v_mul_f32_e32 v33, v65, v37
	v_mul_f32_e32 v34, v5, v37
	v_cvt_pk_bf16_f32 v2, v0, v12
	v_cvt_pk_bf16_f32 v3, v26, v27
	v_cvt_pk_bf16_f32 v4, v13, v29
	v_cvt_pk_bf16_f32 v5, v31, v33
	v_addc_co_u32_e32 v7, vcc, 0, v7, vcc
	v_mul_f32_e32 v8, v8, v47
	v_mul_f32_e32 v9, v9, v49
	v_mul_f32_e32 v10, v10, v51
	global_store_dwordx4 v[6:7], v[2:5], off sc1
	s_nop 1
	v_cvt_pk_bf16_f32 v2, v8, v9
	v_cvt_pk_bf16_f32 v3, v10, v11
	v_cvt_pk_bf16_f32 v4, v28, v30
	v_cvt_pk_bf16_f32 v5, v32, v34
	global_store_dwordx4 v[6:7], v[2:5], off offset:2048 sc1
	s_waitcnt lgkmcnt(0)

; __device__ __forceinline__ void tr_item(const float* __restrict__ W, int ldw, int k0, int n0, bf16* __restrict__ WT, int ldt, int drow, const float* __restrict__ mu, LAS float* scr, int lane, const float* __restrict__ gs = nullptr) {
; #pragma unroll 8
;     for (int i = 0; i < 32; ++i) { const int kk = 2 * i + (lane >> 5); scr[kk * 33 + (lane & 31)] = W[(size_t)(k0 + kk) * ldw + n0 + (lane & 31)]; }
;     asm volatile("s_waitcnt lgkmcnt(0)" ::: "memory");
.LBB0_1450:
	s_lshl_b32 s10, s8, 1
	s_lshl_b32 s11, s5, 1
	v_or_b32_e32 v0, s10, v15
	v_or_b32_e32 v50, s11, v14
	s_add_i32 s12, s10, 4
	s_add_i32 s13, s11, 4
	s_add_i32 s14, s10, 8
	s_add_i32 s15, s11, 8
	s_add_i32 s16, s10, 12
	s_add_i32 s17, s11, 12
	s_add_i32 s18, s10, 16
	s_add_i32 s19, s11, 16
	s_add_i32 s20, s10, 20
	s_add_i32 s21, s11, 20
	s_add_i32 s22, s10, 24
	s_add_i32 s23, s11, 24
	s_add_i32 s10, s10, 28
	s_add_i32 s11, s11, 28
	v_add_u32_e32 v4, s4, v50
	v_or_b32_e32 v51, s12, v15
	v_or_b32_e32 v52, s13, v14
	v_or_b32_e32 v53, s14, v15
	v_or_b32_e32 v54, s15, v14
	v_or_b32_e32 v55, s16, v15
	v_or_b32_e32 v56, s17, v14
	v_or_b32_e32 v57, s18, v15
	v_or_b32_e32 v58, s19, v14
	v_or_b32_e32 v59, s20, v15
	v_or_b32_e32 v60, s21, v14
	v_or_b32_e32 v61, s22, v15
	v_or_b32_e32 v62, s23, v14
	v_or_b32_e32 v63, s10, v15
	v_or_b32_e32 v64, s11, v14
	v_add_u32_e32 v6, s7, v0
	v_mad_u64_u32 v[4:5], s[10:11], v4, s25, v[2:3]
	v_add_u32_e32 v10, s7, v51
	v_add_u32_e32 v8, s4, v52
	v_add_u32_e32 v26, s7, v53
	s_waitcnt lgkmcnt(0)
	v_add_u32_e32 v12, s4, v54
	v_add_u32_e32 v30, s7, v55
	v_add_u32_e32 v28, s4, v56
	v_add_u32_e32 v34, s7, v57
	v_add_u32_e32 v32, s4, v58
	v_add_u32_e32 v40, s7, v59
	v_add_u32_e32 v36, s4, v60
	v_add_u32_e32 v44, s7, v61
	v_add_u32_e32 v42, s4, v62
	v_add_u32_e32 v48, s7, v63
	v_add_u32_e32 v46, s4, v64
	v_mad_u64_u32 v[6:7], s[10:11], v6, s25, v[2:3]
	v_mad_u64_u32 v[8:9], s[10:11], v8, s25, v[2:3]
	v_mad_u64_u32 v[10:11], s[10:11], v10, s25, v[2:3]
	v_mad_u64_u32 v[12:13], s[10:11], v12, s25, v[2:3]
	v_mad_u64_u32 v[26:27], s[10:11], v26, s25, v[2:3]
	v_mad_u64_u32 v[28:29], s[10:11], v28, s25, v[2:3]
	v_mad_u64_u32 v[30:31], s[10:11], v30, s25, v[2:3]
	v_mad_u64_u32 v[32:33], s[10:11], v32, s25, v[2:3]
	v_mad_u64_u32 v[34:35], s[10:11], v34, s25, v[2:3]
	v_mad_u64_u32 v[36:37], s[10:11], v36, s25, v[2:3]
	v_mad_u64_u32 v[40:41], s[10:11], v40, s25, v[2:3]
	v_mad_u64_u32 v[42:43], s[10:11], v42, s25, v[2:3]
	v_mad_u64_u32 v[44:45], s[10:11], v44, s25, v[2:3]
	v_mad_u64_u32 v[46:47], s[10:11], v46, s25, v[2:3]
	v_mad_u64_u32 v[48:49], s[10:11], v48, s25, v[2:3]
	global_load_dword v65, v[4:5], off nt
	global_load_dword v66, v[6:7], off nt
	global_load_dword v67, v[8:9], off nt
	global_load_dword v68, v[10:11], off nt
	global_load_dword v69, v[12:13], off nt
	global_load_dword v70, v[26:27], off nt
	global_load_dword v71, v[28:29], off nt
	global_load_dword v72, v[30:31], off nt
	global_load_dword v73, v[32:33], off nt
	global_load_dword v74, v[34:35], off nt
	global_load_dword v75, v[36:37], off nt
	global_load_dword v76, v[40:41], off nt
	global_load_dword v77, v[42:43], off nt
	global_load_dword v78, v[44:45], off nt
	global_load_dword v79, v[46:47], off nt
	global_load_dword v80, v[48:49], off nt
	s_add_i32 s5, s5, 16
	s_add_i32 s8, s8, 16
	s_add_i32 s9, s9, -16
	v_mad_u64_u32 v[4:5], s[10:11], v50, s26, v[18:19]
	s_cmp_lg_u32 s9, 0
	v_mad_u64_u32 v[6:7], s[10:11], v0, s26, v[18:19]
	v_mad_u64_u32 v[8:9], s[10:11], v52, s26, v[18:19]
	v_mad_u64_u32 v[10:11], s[10:11], v51, s26, v[18:19]
	v_mad_u64_u32 v[12:13], s[10:11], v54, s26, v[18:19]
	v_mad_u64_u32 v[26:27], s[10:11], v53, s26, v[18:19]
	v_mad_u64_u32 v[28:29], s[10:11], v56, s26, v[18:19]
	v_mad_u64_u32 v[30:31], s[10:11], v55, s26, v[18:19]
	v_mad_u64_u32 v[32:33], s[10:11], v58, s26, v[18:19]
	v_mad_u64_u32 v[34:35], s[10:11], v57, s26, v[18:19]
	v_mad_u64_u32 v[36:37], s[10:11], v60, s26, v[18:19]
	v_mad_u64_u32 v[40:41], s[10:11], v59, s26, v[18:19]
	v_mad_u64_u32 v[42:43], s[10:11], v62, s26, v[18:19]
	v_mad_u64_u32 v[44:45], s[10:11], v61, s26, v[18:19]
	v_mad_u64_u32 v[46:47], s[10:11], v64, s26, v[18:19]
	v_mad_u64_u32 v[48:49], s[10:11], v63, s26, v[18:19]
	s_waitcnt vmcnt(15)
	ds_write_b32 v4, v65
	s_waitcnt vmcnt(14)
	ds_write_b32 v6, v66
	s_waitcnt vmcnt(13)
	ds_write_b32 v8, v67
	s_waitcnt vmcnt(12)
	ds_write_b32 v10, v68
	s_waitcnt vmcnt(11)
	ds_write_b32 v12, v69
	s_waitcnt vmcnt(10)
	ds_write_b32 v26, v70
	s_waitcnt vmcnt(9)
	ds_write_b32 v28, v71
	s_waitcnt vmcnt(8)
	ds_write_b32 v30, v72
	s_waitcnt vmcnt(7)
	ds_write_b32 v32, v73
	s_waitcnt vmcnt(6)
	ds_write_b32 v34, v74
	s_waitcnt vmcnt(5)
	ds_write_b32 v36, v75
	s_waitcnt vmcnt(4)
	ds_write_b32 v40, v76
	s_waitcnt vmcnt(3)
	ds_write_b32 v42, v77
	s_waitcnt vmcnt(2)
	ds_write_b32 v44, v78
	s_waitcnt vmcnt(1)
	ds_write_b32 v46, v79
	s_waitcnt vmcnt(0)
	ds_write_b32 v48, v80
	s_cbranch_scc1 .LBB0_1450
; #define LAS __attribute__((address_space(3)))
; __device__ __forceinline__ v4u pack8(const float (&f)[8]) { v4u w; w.x = cvt_pk_bf16(f[0], f[1]); w.y = cvt_pk_bf16(f[2], f[3]); w.z = cvt_pk_bf16(f[4], f[5]); w.w = cvt_pk_bf16(f[6], f[7]); return w; }
; __device__ __forceinline__ void tr_item(const float* __restrict__ W, int ldw, int k0, int n0, bf16* __restrict__ WT, int ldt, int drow, const float* __restrict__ mu, LAS float* scr, int lane, const float* __restrict__ gs = nullptr) {
;     ...
;     if (mu) {
; #pragma unroll
;         for (int e = 0; e < 8; ++e) mv[e] = mu[k0 + 8 * c + e];
;     } else if (gs) {
; #pragma unroll
;         for (int e = 0; e < 8; ++e) mv[e] = gs[k0 + 8 * c + e];
;     }
; #pragma unroll
;     for (int j = 0; j < 4; ++j) {
;         const int n = (lane >> 3) + 8 * j; const LAS float* s = scr + (8 * c) * 33 + n;
;         float f[8];
; #pragma unroll
;         for (int e = 0; e < 8; ++e) f[e] = s[e * 33];
;         bf16* dp = WT + (size_t)(drow + n) * ldt + k0 + 8 * c;
;         if (mu) {
;             float f1[8], f2[8];
; #pragma unroll
;             for (int e = 0; e < 8; ++e) { f1[e] = f[e] * (1.f - mv[e]); f2[e] = f[e] * mv[e]; }
;             *(v4u*)dp = pack8(f1); *(v4u*)(dp + 1024) = pack8(f2);
;         } else { if (gs) {
; #pragma unroll
;             for (int e = 0; e < 8; ++e) f[e] *= mv[e]; }
;             *(v4u*)dp = pack8(f); }
;     }
; __device__ __forceinline__ void ph_p0(const Params& p, LAS unsigned char* lds, int tid, int lane, int wave) {
;     ...
;         if (r < C_G1) { const int j = r / 80, q = r % 80, kb = q / 5, nb = q % 5;
;             tr_item(p.in[I_G1] + (size_t)j * D * LG, LG, 64 * kb, 32 * nb, (bf16*)(ws + WS_WRW + j * SZ_WRW), KRW, 3200 + 32 * nb, p.in[I_MU] + (size_t)(j * 6 + 5) * D, scr, lane); continue; }
	s_and_b64 s[8:9], s[0:1], exec
	s_cselect_b32 s5, 0xe00000, 0
	s_add_u32 s5, s36, s5
	s_addc_u32 s7, s37, 0
	s_and_b64 s[0:1], s[0:1], exec
	s_mov_b32 s0, 0xb000
	s_cselect_b32 s1, s0, 0x5000
	s_add_i32 s0, s94, 0xc80
	s_add_u32 s8, s50, s1
	s_addc_u32 s9, s51, 0
	v_or_b32_e32 v0, s4, v20
	s_waitcnt lgkmcnt(0)
	v_lshl_add_u64 v[6:7], v[0:1], 2, s[8:9]
	global_load_dwordx4 v[2:5], v[6:7], off
	s_nop 0
	global_load_dwordx4 v[6:9], v[6:7], off offset:16
	ds_read2_b32 v[26:27], v19 offset0:33 offset1:41
	ds_read2_b32 v[28:29], v19 offset0:66 offset1:74
	ds_read2_b32 v[30:31], v19 offset0:99 offset1:107
	ds_read2_b32 v[32:33], v19 offset0:132 offset1:140
	ds_read2_b32 v[34:35], v19 offset0:165 offset1:173
	ds_read2_b32 v[36:37], v19 offset0:198 offset1:206
	ds_read2_b32 v[40:41], v19 offset0:231 offset1:239
	ds_read2_b32 v[42:43], v19 offset1:8
	s_lshl_b32 s1, s4, 1
	s_add_u32 s4, s5, s1
	v_or_b32_e32 v10, s0, v17
	v_lshlrev_b32_e32 v0, 1, v20
	s_addc_u32 s5, s7, 0
	v_or_b32_e32 v11, s0, v21
	v_lshl_add_u64 v[44:45], s[4:5], 0, v[0:1]
	v_lshlrev_b32_e32 v0, 12, v10
	v_lshl_add_u64 v[46:47], v[44:45], 0, v[0:1]
	v_lshlrev_b32_e32 v0, 12, v11
	v_lshl_add_u64 v[48:49], v[44:45], 0, v[0:1]
	s_waitcnt vmcnt(1)
	v_sub_f32_e32 v50, 1.0, v2
	s_waitcnt lgkmcnt(0)
	v_mul_f32_e32 v0, v2, v42
	v_sub_f32_e32 v51, 1.0, v3
	v_mul_f32_e32 v10, v3, v26
	v_sub_f32_e32 v52, 1.0, v4
	v_mul_f32_e32 v11, v4, v28
	v_mul_f32_e32 v12, v5, v30
	s_waitcnt vmcnt(0)
	v_sub_f32_e32 v54, 1.0, v6
	v_mul_f32_e32 v13, v6, v32
	v_mul_f32_e32 v56, v7, v34
	v_sub_f32_e32 v53, 1.0, v5
	v_sub_f32_e32 v55, 1.0, v7
	v_sub_f32_e32 v57, 1.0, v8
	v_mul_f32_e32 v58, v8, v36
	v_sub_f32_e32 v59, 1.0, v9
	v_mul_f32_e32 v60, v9, v40
	v_mul_f32_e32 v61, v2, v43
	v_mul_f32_e32 v62, v3, v27
	v_mul_f32_e32 v63, v4, v29
	v_mul_f32_e32 v64, v5, v31
	v_mul_f32_e32 v65, v6, v33
	v_mul_f32_e32 v66, v7, v35
	v_mul_f32_e32 v67, v8, v37
	v_mul_f32_e32 v68, v9, v41
	v_mul_f32_e32 v69, v51, v26
	v_mul_f32_e32 v70, v52, v28
	v_mul_f32_e32 v32, v54, v32
	v_cvt_pk_bf16_f32 v10, v0, v10
	v_cvt_pk_bf16_f32 v11, v11, v12
	v_cvt_pk_bf16_f32 v12, v13, v56
	v_cvt_pk_bf16_f32 v13, v58, v60
	v_mul_f32_e32 v0, v50, v43
	v_mul_f32_e32 v43, v51, v27
	v_mul_f32_e32 v56, v52, v29
	v_cvt_pk_bf16_f32 v26, v61, v62
	v_cvt_pk_bf16_f32 v27, v63, v64
	v_cvt_pk_bf16_f32 v28, v65, v66
	v_cvt_pk_bf16_f32 v29, v67, v68
	v_mul_f32_e32 v42, v50, v42
	v_mul_f32_e32 v71, v53, v30
	v_mul_f32_e32 v34, v55, v34
	v_mul_f32_e32 v36, v57, v36
	v_mul_f32_e32 v40, v59, v40
	v_mul_f32_e32 v58, v53, v31
	v_mul_f32_e32 v60, v54, v33
	v_mul_f32_e32 v35, v55, v35
	v_mul_f32_e32 v37, v57, v37
	v_mul_f32_e32 v41, v59, v41
	v_cvt_pk_bf16_f32 v30, v42, v69
	v_cvt_pk_bf16_f32 v31, v70, v71
	v_cvt_pk_bf16_f32 v32, v32, v34
	v_cvt_pk_bf16_f32 v33, v36, v40
	global_store_dwordx4 v[46:47], v[10:13], off offset:2048 sc1
	s_nop 1
	v_cvt_pk_bf16_f32 v10, v0, v43
	v_cvt_pk_bf16_f32 v11, v56, v58
	v_cvt_pk_bf16_f32 v12, v60, v35
	v_cvt_pk_bf16_f32 v13, v37, v41
	global_store_dwordx4 v[48:49], v[26:29], off offset:2048 sc1
	global_store_dwordx4 v[46:47], v[30:33], off sc1
	global_store_dwordx4 v[48:49], v[10:13], off sc1
	ds_read2_b32 v[26:27], v19 offset0:16 offset1:24
	ds_read2_b32 v[28:29], v19 offset0:49 offset1:57
	ds_read2_b32 v[30:31], v19 offset0:82 offset1:90
	ds_read2_b32 v[32:33], v19 offset0:115 offset1:123
	ds_read2_b32 v[34:35], v19 offset0:148 offset1:156
	ds_read2_b32 v[36:37], v19 offset0:181 offset1:189
	ds_read2_b32 v[40:41], v19 offset0:214 offset1:222
	ds_read2_b32 v[42:43], v19 offset0:247 offset1:255
	v_or_b32_e32 v0, s0, v38
	v_lshlrev_b32_e32 v0, 12, v0
	v_lshl_add_u64 v[46:47], v[44:45], 0, v[0:1]
	s_waitcnt lgkmcnt(7)
	v_mul_f32_e32 v0, v50, v26
	s_waitcnt lgkmcnt(6)
	v_mul_f32_e32 v10, v51, v28
	s_waitcnt lgkmcnt(5)
	v_mul_f32_e32 v11, v52, v30
	s_waitcnt lgkmcnt(4)
	v_mul_f32_e32 v12, v53, v32
	s_waitcnt lgkmcnt(3)
	v_mul_f32_e32 v13, v54, v34
	s_waitcnt lgkmcnt(2)
	v_mul_f32_e32 v48, v55, v36
	s_waitcnt lgkmcnt(1)
	v_mul_f32_e32 v49, v57, v40
	s_waitcnt lgkmcnt(0)
	v_mul_f32_e32 v56, v59, v42
	v_cvt_pk_bf16_f32 v10, v0, v10
	v_cvt_pk_bf16_f32 v11, v11, v12
	v_cvt_pk_bf16_f32 v12, v13, v48
	v_cvt_pk_bf16_f32 v13, v49, v56
	v_or_b32_e32 v0, s0, v39
	v_mul_f32_e32 v26, v2, v26
	v_mul_f32_e32 v28, v3, v28
	v_mul_f32_e32 v30, v4, v30
	v_mul_f32_e32 v32, v5, v32
	v_mul_f32_e32 v34, v6, v34
	v_mul_f32_e32 v36, v7, v36
	v_mul_f32_e32 v40, v8, v40
	v_mul_f32_e32 v42, v9, v42
	global_store_dwordx4 v[46:47], v[10:13], off sc1
	v_lshlrev_b32_e32 v0, 12, v0
	v_mul_f32_e32 v6, v6, v35
	v_cvt_pk_bf16_f32 v10, v26, v28
	v_cvt_pk_bf16_f32 v11, v30, v32
	v_cvt_pk_bf16_f32 v12, v34, v36
	v_cvt_pk_bf16_f32 v13, v40, v42
	global_store_dwordx4 v[46:47], v[10:13], off offset:2048 sc1
	v_mul_f32_e32 v26, v4, v31
	v_mul_f32_e32 v4, v53, v33
	v_lshl_add_u64 v[10:11], v[44:45], 0, v[0:1]
	v_mul_f32_e32 v0, v50, v27
	v_mul_f32_e32 v12, v2, v27
	v_mul_f32_e32 v2, v51, v29
	v_mul_f32_e32 v13, v3, v29
	v_mul_f32_e32 v3, v52, v31
	v_mul_f32_e32 v27, v5, v33
	v_mul_f32_e32 v5, v54, v35
	v_mul_f32_e32 v28, v55, v37
	v_mul_f32_e32 v29, v57, v41
	v_mul_f32_e32 v30, v59, v43
	v_cvt_pk_bf16_f32 v2, v0, v2
	v_cvt_pk_bf16_f32 v3, v3, v4
	v_cvt_pk_bf16_f32 v4, v5, v28
	v_cvt_pk_bf16_f32 v5, v29, v30
	v_mul_f32_e32 v7, v7, v37
	v_mul_f32_e32 v8, v8, v41
	v_mul_f32_e32 v9, v9, v43
	global_store_dwordx4 v[10:11], v[2:5], off sc1
	s_nop 1
	v_cvt_pk_bf16_f32 v2, v12, v13
	v_cvt_pk_bf16_f32 v3, v26, v27
	v_cvt_pk_bf16_f32 v4, v6, v7
	v_cvt_pk_bf16_f32 v5, v8, v9
	global_store_dwordx4 v[10:11], v[2:5], off offset:2048 sc1
	s_waitcnt lgkmcnt(0)

; __device__ __forceinline__ void tr_item(const float* __restrict__ W, int ldw, int k0, int n0, bf16* __restrict__ WT, int ldt, int drow, const float* __restrict__ mu, LAS float* scr, int lane, const float* __restrict__ gs = nullptr) {
; #pragma unroll 8
;     for (int i = 0; i < 32; ++i) { const int kk = 2 * i + (lane >> 5); scr[kk * 33 + (lane & 31)] = W[(size_t)(k0 + kk) * ldw + n0 + (lane & 31)]; }
;     asm volatile("s_waitcnt lgkmcnt(0)" ::: "memory");
.LBB0_1455:
	s_lshl_b32 s9, s7, 1
	s_lshl_b32 s10, s8, 1
	v_or_b32_e32 v41, s10, v14
	s_add_i32 s11, s9, 4
	s_add_i32 s12, s10, 4
	s_add_i32 s14, s10, 8
	v_add_u32_e32 v0, s0, v41
	v_or_b32_e32 v42, s11, v15
	v_or_b32_e32 v43, s12, v14
	v_mov_b32_e32 v7, v1
	v_or_b32_e32 v40, s9, v15
	s_add_i32 s16, s10, 12
	v_or_b32_e32 v45, s14, v14
	s_waitcnt lgkmcnt(3)
	v_lshlrev_b64 v[32:33], 8, v[0:1]
	v_add_u32_e32 v6, s5, v42
	v_add_u32_e32 v0, s0, v43
	v_mov_b32_e32 v5, v1
	s_add_i32 s13, s9, 8
	s_add_i32 s15, s9, 12
	s_add_i32 s18, s10, 16
	v_add_u32_e32 v4, s5, v40
	v_or_b32_e32 v47, s16, v14
	v_lshlrev_b64 v[6:7], 8, v[6:7]
	v_lshlrev_b64 v[34:35], 8, v[0:1]
	v_add_u32_e32 v0, s0, v45
	s_add_i32 s20, s10, 20
	v_or_b32_e32 v44, s13, v15
	v_or_b32_e32 v46, s15, v15
	v_or_b32_e32 v49, s18, v14
	v_lshlrev_b64 v[4:5], 8, v[4:5]
	v_lshl_add_u64 v[32:33], v[2:3], 0, v[32:33]
	v_lshl_add_u64 v[6:7], v[2:3], 0, v[6:7]
	v_lshlrev_b64 v[36:37], 8, v[0:1]
	v_add_u32_e32 v0, s0, v47
	v_mov_b32_e32 v9, v1
	v_mov_b32_e32 v11, v1
	s_add_i32 s17, s9, 16
	s_add_i32 s19, s9, 20
	s_add_i32 s22, s10, 24
	v_or_b32_e32 v51, s20, v14
	v_add_u32_e32 v8, s5, v44
	v_add_u32_e32 v10, s5, v46
	v_lshl_add_u64 v[4:5], v[2:3], 0, v[4:5]
	v_lshl_add_u64 v[34:35], v[2:3], 0, v[34:35]
	global_load_dword v56, v[32:33], off nt
	global_load_dword v57, v[4:5], off nt
	global_load_dword v58, v[34:35], off nt
	global_load_dword v59, v[6:7], off nt
	v_lshlrev_b64 v[6:7], 8, v[0:1]
	v_add_u32_e32 v0, s0, v49
	s_add_i32 s21, s9, 24
	s_add_i32 s9, s9, 28
	s_add_i32 s10, s10, 28
	v_or_b32_e32 v48, s17, v15
	v_or_b32_e32 v50, s19, v15
	v_or_b32_e32 v53, s22, v14
	v_lshlrev_b64 v[8:9], 8, v[8:9]
	v_lshlrev_b64 v[10:11], 8, v[10:11]
	v_lshl_add_u64 v[4:5], v[2:3], 0, v[36:37]
	v_lshl_add_u64 v[6:7], v[2:3], 0, v[6:7]
	v_lshlrev_b64 v[32:33], 8, v[0:1]
	v_add_u32_e32 v0, s0, v51
	s_waitcnt lgkmcnt(0)
	v_mov_b32_e32 v13, v1
	v_mov_b32_e32 v27, v1
	v_or_b32_e32 v52, s21, v15
	v_or_b32_e32 v54, s9, v15
	v_or_b32_e32 v55, s10, v14
	v_add_u32_e32 v12, s5, v48
	v_add_u32_e32 v26, s5, v50
	v_lshl_add_u64 v[8:9], v[2:3], 0, v[8:9]
	v_lshl_add_u64 v[10:11], v[2:3], 0, v[10:11]
	global_load_dword v60, v[4:5], off nt
	global_load_dword v61, v[8:9], off nt
	global_load_dword v62, v[6:7], off nt
	global_load_dword v63, v[10:11], off nt
	v_lshlrev_b64 v[6:7], 8, v[0:1]
	v_add_u32_e32 v0, s0, v53
	v_mov_b32_e32 v29, v1
	v_mov_b32_e32 v31, v1
	v_add_u32_e32 v28, s5, v52
	v_add_u32_e32 v30, s5, v54
	v_lshlrev_b64 v[12:13], 8, v[12:13]
	v_lshlrev_b64 v[26:27], 8, v[26:27]
	v_lshl_add_u64 v[4:5], v[2:3], 0, v[32:33]
	v_lshl_add_u64 v[6:7], v[2:3], 0, v[6:7]
	v_lshlrev_b64 v[8:9], 8, v[0:1]
	v_add_u32_e32 v0, s0, v55
	v_lshlrev_b64 v[28:29], 8, v[28:29]
	v_lshlrev_b64 v[30:31], 8, v[30:31]
	v_lshl_add_u64 v[12:13], v[2:3], 0, v[12:13]
	v_lshl_add_u64 v[26:27], v[2:3], 0, v[26:27]
	global_load_dword v64, v[4:5], off nt
	global_load_dword v65, v[12:13], off nt
	global_load_dword v66, v[6:7], off nt
	global_load_dword v67, v[26:27], off nt
	v_lshl_add_u64 v[4:5], v[2:3], 0, v[8:9]
	v_lshlrev_b64 v[6:7], 8, v[0:1]
	v_lshl_add_u64 v[28:29], v[2:3], 0, v[28:29]
	v_lshl_add_u64 v[30:31], v[2:3], 0, v[30:31]
	v_lshl_add_u64 v[6:7], v[2:3], 0, v[6:7]
	global_load_dword v0, v[4:5], off nt
	global_load_dword v68, v[28:29], off nt
	global_load_dword v69, v[6:7], off nt
	global_load_dword v70, v[30:31], off nt
	s_add_i32 s8, s8, 16
	s_add_i32 s7, s7, 16
	s_add_i32 s4, s4, -16
	v_mad_u64_u32 v[4:5], s[10:11], v41, s26, v[18:19]
	s_cmp_lg_u32 s4, 0
	v_mad_u64_u32 v[6:7], s[10:11], v40, s26, v[18:19]
	v_mad_u64_u32 v[8:9], s[10:11], v43, s26, v[18:19]
	v_mad_u64_u32 v[10:11], s[10:11], v42, s26, v[18:19]
	v_mad_u64_u32 v[12:13], s[10:11], v45, s26, v[18:19]
	v_mad_u64_u32 v[26:27], s[10:11], v44, s26, v[18:19]
	v_mad_u64_u32 v[28:29], s[10:11], v47, s26, v[18:19]
	v_mad_u64_u32 v[30:31], s[10:11], v46, s26, v[18:19]
	v_mad_u64_u32 v[32:33], s[10:11], v49, s26, v[18:19]
	v_mad_u64_u32 v[34:35], s[10:11], v48, s26, v[18:19]
	v_mad_u64_u32 v[36:37], s[10:11], v51, s26, v[18:19]
	v_mad_u64_u32 v[40:41], s[10:11], v50, s26, v[18:19]
	v_mad_u64_u32 v[42:43], s[10:11], v53, s26, v[18:19]
	v_mad_u64_u32 v[44:45], s[10:11], v52, s26, v[18:19]
	v_mad_u64_u32 v[46:47], s[10:11], v55, s26, v[18:19]
	v_mad_u64_u32 v[48:49], s[10:11], v54, s26, v[18:19]
	s_waitcnt vmcnt(15)
	ds_write_b32 v4, v56
	s_waitcnt vmcnt(14)
	ds_write_b32 v6, v57
	s_waitcnt vmcnt(13)
	ds_write_b32 v8, v58
	s_waitcnt vmcnt(12)
	ds_write_b32 v10, v59
	s_waitcnt vmcnt(11)
	ds_write_b32 v12, v60
	s_waitcnt vmcnt(10)
	ds_write_b32 v26, v61
	s_waitcnt vmcnt(9)
	ds_write_b32 v28, v62
	s_waitcnt vmcnt(8)
	ds_write_b32 v30, v63
	s_waitcnt vmcnt(7)
	ds_write_b32 v32, v64
	s_waitcnt vmcnt(6)
	ds_write_b32 v34, v65
	s_waitcnt vmcnt(5)
	ds_write_b32 v36, v66
	s_waitcnt vmcnt(4)
	ds_write_b32 v40, v67
	s_waitcnt vmcnt(3)
	ds_write_b32 v42, v0
	s_waitcnt vmcnt(2)
	ds_write_b32 v44, v68
	s_waitcnt vmcnt(1)
	ds_write_b32 v46, v69
	s_waitcnt vmcnt(0)
	ds_write_b32 v48, v70
	s_cbranch_scc1 .LBB0_1455
; #define LAS __attribute__((address_space(3)))
; __device__ __forceinline__ v4u pack8(const float (&f)[8]) { v4u w; w.x = cvt_pk_bf16(f[0], f[1]); w.y = cvt_pk_bf16(f[2], f[3]); w.z = cvt_pk_bf16(f[4], f[5]); w.w = cvt_pk_bf16(f[6], f[7]); return w; }
; __device__ __forceinline__ void tr_item(const float* __restrict__ W, int ldw, int k0, int n0, bf16* __restrict__ WT, int ldt, int drow, const float* __restrict__ mu, LAS float* scr, int lane, const float* __restrict__ gs = nullptr) {
;     ...
;     if (mu) {
; #pragma unroll
;         for (int e = 0; e < 8; ++e) mv[e] = mu[k0 + 8 * c + e];
;     } else if (gs) {
; #pragma unroll
;         for (int e = 0; e < 8; ++e) mv[e] = gs[k0 + 8 * c + e];
;     }
; #pragma unroll
;     for (int j = 0; j < 4; ++j) {
;         const int n = (lane >> 3) + 8 * j; const LAS float* s = scr + (8 * c) * 33 + n;
;         float f[8];
; #pragma unroll
;         for (int e = 0; e < 8; ++e) f[e] = s[e * 33];
;         bf16* dp = WT + (size_t)(drow + n) * ldt + k0 + 8 * c;
;         if (mu) {
;             float f1[8], f2[8];
; #pragma unroll
;             for (int e = 0; e < 8; ++e) { f1[e] = f[e] * (1.f - mv[e]); f2[e] = f[e] * mv[e]; }
;             *(v4u*)dp = pack8(f1); *(v4u*)(dp + 1024) = pack8(f2);
;         } else { if (gs) {
; #pragma unroll
;             for (int e = 0; e < 8; ++e) f[e] *= mv[e]; }
;             *(v4u*)dp = pack8(f); }
;     }
; __device__ __forceinline__ void ph_p0(const Params& p, LAS unsigned char* lds, int tid, int lane, int wave) {
;     ...
;         if (r < C_A1) { const int j = r / 32, q = r % 32, kb = q / 2, nb = q % 2;
;             tr_item(p.in[I_A1] + (size_t)j * D * LA, LA, 64 * kb, 32 * nb, (bf16*)(ws + WS_WRW + j * SZ_WRW), KRW, 3136 + 32 * nb, p.in[I_MU] + (size_t)(j * 6 + 4) * D, scr, lane); continue; }
	s_mul_i32 s7, s94, 6
	s_mul_hi_u32 s4, s94, 0xe00000
	s_mul_i32 s5, s94, 0xe00000
	s_add_i32 s94, s7, 4
	s_add_u32 s7, s36, s5
	s_addc_u32 s8, s37, s4
	s_lshl_b64 s[4:5], s[94:95], 12
	s_or_b32 s1, s1, 0xc40
	s_add_u32 s4, s50, s4
	v_or_b32_e32 v0, s0, v20
	s_addc_u32 s5, s51, s5
	s_waitcnt lgkmcnt(0)
	v_lshlrev_b32_e32 v0, 2, v0
	global_load_dwordx4 v[2:5], v0, s[4:5]
	global_load_dwordx4 v[6:9], v0, s[4:5] offset:16
	ds_read2_b32 v[26:27], v19 offset0:33 offset1:41
	ds_read2_b32 v[28:29], v19 offset0:66 offset1:74
	ds_read2_b32 v[30:31], v19 offset0:99 offset1:107
	ds_read2_b32 v[32:33], v19 offset0:132 offset1:140
	ds_read2_b32 v[34:35], v19 offset0:165 offset1:173
	ds_read2_b32 v[36:37], v19 offset0:198 offset1:206
	ds_read2_b32 v[40:41], v19 offset0:231 offset1:239
	ds_read2_b32 v[42:43], v19 offset1:8
	s_lshl_b32 s0, s0, 1
	s_add_u32 s4, s7, s0
	v_lshlrev_b32_e32 v0, 1, v20
	v_or_b32_e32 v10, s1, v17
	s_addc_u32 s5, s8, 0
	v_or_b32_e32 v11, s1, v21
	v_lshl_add_u64 v[44:45], s[4:5], 0, v[0:1]
	v_lshlrev_b32_e32 v0, 12, v10
	v_lshl_add_u64 v[46:47], v[44:45], 0, v[0:1]
	v_lshlrev_b32_e32 v0, 12, v11
	v_lshl_add_u64 v[48:49], v[44:45], 0, v[0:1]
	s_waitcnt vmcnt(1)
	v_sub_f32_e32 v53, 1.0, v5
	v_sub_f32_e32 v50, 1.0, v2
	s_waitcnt lgkmcnt(0)
	v_mul_f32_e32 v0, v2, v42
	v_sub_f32_e32 v51, 1.0, v3
	v_mul_f32_e32 v10, v3, v26
	v_sub_f32_e32 v52, 1.0, v4
	v_mul_f32_e32 v11, v4, v28
	v_mul_f32_e32 v12, v5, v30
	s_waitcnt vmcnt(0)
	v_sub_f32_e32 v54, 1.0, v6
	v_mul_f32_e32 v13, v6, v32
	v_sub_f32_e32 v55, 1.0, v7
	v_mul_f32_e32 v56, v7, v34
	v_sub_f32_e32 v57, 1.0, v8
	v_sub_f32_e32 v59, 1.0, v9
	v_mul_f32_e32 v30, v53, v30
	v_mul_f32_e32 v58, v8, v36
	v_mul_f32_e32 v60, v9, v40
	v_mul_f32_e32 v61, v2, v43
	v_mul_f32_e32 v62, v3, v27
	v_mul_f32_e32 v63, v4, v29
	v_mul_f32_e32 v64, v5, v31
	v_mul_f32_e32 v42, v50, v42
	v_mul_f32_e32 v69, v51, v26
	v_mul_f32_e32 v70, v52, v28
	v_mul_f32_e32 v32, v54, v32
	v_mul_f32_e32 v34, v55, v34
	v_mul_f32_e32 v36, v57, v36
	v_mul_f32_e32 v40, v59, v40
	v_cvt_pk_bf16_f32 v10, v0, v10
	v_cvt_pk_bf16_f32 v11, v11, v12
	v_cvt_pk_bf16_f32 v12, v13, v56
	v_cvt_pk_bf16_f32 v13, v58, v60
	v_mul_f32_e32 v0, v50, v43
	v_mul_f32_e32 v27, v51, v27
	v_mul_f32_e32 v43, v52, v29
	v_mul_f32_e32 v56, v53, v31
	v_cvt_pk_bf16_f32 v28, v42, v69
	v_cvt_pk_bf16_f32 v29, v70, v30
	v_cvt_pk_bf16_f32 v30, v32, v34
	v_cvt_pk_bf16_f32 v31, v36, v40
	v_mul_f32_e32 v65, v6, v33
	v_mul_f32_e32 v66, v7, v35
	v_mul_f32_e32 v67, v8, v37
	v_mul_f32_e32 v68, v9, v41
	v_mul_f32_e32 v33, v54, v33
	v_mul_f32_e32 v35, v55, v35
	v_mul_f32_e32 v37, v57, v37
	v_mul_f32_e32 v41, v59, v41
	v_cvt_pk_bf16_f32 v26, v61, v62
	global_store_dwordx4 v[46:47], v[10:13], off offset:2048 sc1
	s_nop 1
	v_cvt_pk_bf16_f32 v10, v0, v27
	v_cvt_pk_bf16_f32 v11, v43, v56
	v_cvt_pk_bf16_f32 v12, v33, v35
	v_cvt_pk_bf16_f32 v13, v37, v41
	global_store_dwordx4 v[46:47], v[28:31], off sc1
	global_store_dwordx4 v[48:49], v[10:13], off sc1
	v_cvt_pk_bf16_f32 v27, v63, v64
	v_or_b32_e32 v0, s1, v38
	v_cvt_pk_bf16_f32 v28, v65, v66
	v_cvt_pk_bf16_f32 v29, v67, v68
	global_store_dwordx4 v[48:49], v[26:29], off offset:2048 sc1
	ds_read2_b32 v[26:27], v19 offset0:16 offset1:24
	ds_read2_b32 v[28:29], v19 offset0:49 offset1:57
	ds_read2_b32 v[30:31], v19 offset0:82 offset1:90
	ds_read2_b32 v[32:33], v19 offset0:115 offset1:123
	ds_read2_b32 v[34:35], v19 offset0:148 offset1:156
	ds_read2_b32 v[36:37], v19 offset0:181 offset1:189
	ds_read2_b32 v[40:41], v19 offset0:214 offset1:222
	ds_read2_b32 v[42:43], v19 offset0:247 offset1:255
	v_lshlrev_b32_e32 v0, 12, v0
	v_lshl_add_u64 v[46:47], v[44:45], 0, v[0:1]
	s_waitcnt lgkmcnt(7)
	v_mul_f32_e32 v0, v50, v26
	s_waitcnt lgkmcnt(6)
	v_mul_f32_e32 v10, v51, v28
	s_waitcnt lgkmcnt(5)
	v_mul_f32_e32 v11, v52, v30
	s_waitcnt lgkmcnt(4)
	v_mul_f32_e32 v12, v53, v32
	s_waitcnt lgkmcnt(3)
	v_mul_f32_e32 v13, v54, v34
	s_waitcnt lgkmcnt(2)
	v_mul_f32_e32 v48, v55, v36
	s_waitcnt lgkmcnt(1)
	v_mul_f32_e32 v49, v57, v40
	s_waitcnt lgkmcnt(0)
	v_mul_f32_e32 v56, v59, v42
	v_cvt_pk_bf16_f32 v10, v0, v10
	v_cvt_pk_bf16_f32 v11, v11, v12
	v_cvt_pk_bf16_f32 v12, v13, v48
	v_cvt_pk_bf16_f32 v13, v49, v56
	v_or_b32_e32 v0, s1, v39
	v_mul_f32_e32 v26, v2, v26
	v_mul_f32_e32 v28, v3, v28
	v_mul_f32_e32 v30, v4, v30
	v_mul_f32_e32 v32, v5, v32
	v_mul_f32_e32 v34, v6, v34
	v_mul_f32_e32 v36, v7, v36
	v_mul_f32_e32 v40, v8, v40
	v_mul_f32_e32 v42, v9, v42
	global_store_dwordx4 v[46:47], v[10:13], off sc1
	v_lshlrev_b32_e32 v0, 12, v0
	v_mul_f32_e32 v6, v6, v35
	v_cvt_pk_bf16_f32 v10, v26, v28
	v_cvt_pk_bf16_f32 v11, v30, v32
	v_cvt_pk_bf16_f32 v12, v34, v36
	v_cvt_pk_bf16_f32 v13, v40, v42
	global_store_dwordx4 v[46:47], v[10:13], off offset:2048 sc1
	v_mul_f32_e32 v26, v4, v31
	v_mul_f32_e32 v4, v53, v33
	v_lshl_add_u64 v[10:11], v[44:45], 0, v[0:1]
	v_mul_f32_e32 v0, v50, v27
	v_mul_f32_e32 v12, v2, v27
	v_mul_f32_e32 v2, v51, v29
	v_mul_f32_e32 v13, v3, v29
	v_mul_f32_e32 v3, v52, v31
	v_mul_f32_e32 v27, v5, v33
	v_mul_f32_e32 v5, v54, v35
	v_mul_f32_e32 v28, v55, v37
	v_mul_f32_e32 v29, v57, v41
	v_mul_f32_e32 v30, v59, v43
	v_cvt_pk_bf16_f32 v2, v0, v2
	v_cvt_pk_bf16_f32 v3, v3, v4
	v_cvt_pk_bf16_f32 v4, v5, v28
	v_cvt_pk_bf16_f32 v5, v29, v30
	v_mul_f32_e32 v7, v7, v37
	v_mul_f32_e32 v8, v8, v41
	v_mul_f32_e32 v9, v9, v43
	global_store_dwordx4 v[10:11], v[2:5], off sc1
	s_nop 1
	v_cvt_pk_bf16_f32 v2, v12, v13
	v_cvt_pk_bf16_f32 v3, v26, v27
	v_cvt_pk_bf16_f32 v4, v6, v7
	v_cvt_pk_bf16_f32 v5, v8, v9
	global_store_dwordx4 v[10:11], v[2:5], off offset:2048 sc1
	s_waitcnt lgkmcnt(0)

; __device__ __forceinline__ void tr_item(const float* __restrict__ W, int ldw, int k0, int n0, bf16* __restrict__ WT, int ldt, int drow, const float* __restrict__ mu, LAS float* scr, int lane, const float* __restrict__ gs = nullptr) {
; #pragma unroll 8
;     for (int i = 0; i < 32; ++i) { const int kk = 2 * i + (lane >> 5); scr[kk * 33 + (lane & 31)] = W[(size_t)(k0 + kk) * ldw + n0 + (lane & 31)]; }
;     asm volatile("s_waitcnt lgkmcnt(0)" ::: "memory");
.LBB0_1460:
	s_lshl_b32 s9, s7, 1
	s_lshl_b32 s10, s8, 1
	v_or_b32_e32 v41, s10, v14
	s_add_i32 s11, s9, 4
	s_add_i32 s12, s10, 4
	s_add_i32 s14, s10, 8
	v_add_u32_e32 v0, s0, v41
	v_or_b32_e32 v42, s11, v15
	v_or_b32_e32 v43, s12, v14
	v_mov_b32_e32 v7, v1
	v_or_b32_e32 v40, s9, v15
	s_add_i32 s16, s10, 12
	v_or_b32_e32 v45, s14, v14
	s_waitcnt lgkmcnt(3)
	v_lshlrev_b64 v[32:33], 8, v[0:1]
	v_add_u32_e32 v6, s5, v42
	v_add_u32_e32 v0, s0, v43
	v_mov_b32_e32 v5, v1
	s_add_i32 s13, s9, 8
	s_add_i32 s15, s9, 12
	s_add_i32 s18, s10, 16
	v_add_u32_e32 v4, s5, v40
	v_or_b32_e32 v47, s16, v14
	v_lshlrev_b64 v[6:7], 8, v[6:7]
	v_lshlrev_b64 v[34:35], 8, v[0:1]
	v_add_u32_e32 v0, s0, v45
	s_add_i32 s20, s10, 20
	v_or_b32_e32 v44, s13, v15
	v_or_b32_e32 v46, s15, v15
	v_or_b32_e32 v49, s18, v14
	v_lshlrev_b64 v[4:5], 8, v[4:5]
	v_lshl_add_u64 v[32:33], v[2:3], 0, v[32:33]
	v_lshl_add_u64 v[6:7], v[2:3], 0, v[6:7]
	v_lshlrev_b64 v[36:37], 8, v[0:1]
	v_add_u32_e32 v0, s0, v47
	v_mov_b32_e32 v9, v1
	v_mov_b32_e32 v11, v1
	s_add_i32 s17, s9, 16
	s_add_i32 s19, s9, 20
	s_add_i32 s22, s10, 24
	v_or_b32_e32 v51, s20, v14
	v_add_u32_e32 v8, s5, v44
	v_add_u32_e32 v10, s5, v46
	v_lshl_add_u64 v[4:5], v[2:3], 0, v[4:5]
	v_lshl_add_u64 v[34:35], v[2:3], 0, v[34:35]
	global_load_dword v56, v[32:33], off nt
	global_load_dword v57, v[4:5], off nt
	global_load_dword v58, v[34:35], off nt
	global_load_dword v59, v[6:7], off nt
	v_lshlrev_b64 v[6:7], 8, v[0:1]
	v_add_u32_e32 v0, s0, v49
	s_add_i32 s21, s9, 24
	s_add_i32 s9, s9, 28
	s_add_i32 s10, s10, 28
	v_or_b32_e32 v48, s17, v15
	v_or_b32_e32 v50, s19, v15
	v_or_b32_e32 v53, s22, v14
	v_lshlrev_b64 v[8:9], 8, v[8:9]
	v_lshlrev_b64 v[10:11], 8, v[10:11]
	v_lshl_add_u64 v[4:5], v[2:3], 0, v[36:37]
	v_lshl_add_u64 v[6:7], v[2:3], 0, v[6:7]
	v_lshlrev_b64 v[32:33], 8, v[0:1]
	v_add_u32_e32 v0, s0, v51
	s_waitcnt lgkmcnt(0)
	v_mov_b32_e32 v13, v1
	v_mov_b32_e32 v27, v1
	v_or_b32_e32 v52, s21, v15
	v_or_b32_e32 v54, s9, v15
	v_or_b32_e32 v55, s10, v14
	v_add_u32_e32 v12, s5, v48
	v_add_u32_e32 v26, s5, v50
	v_lshl_add_u64 v[8:9], v[2:3], 0, v[8:9]
	v_lshl_add_u64 v[10:11], v[2:3], 0, v[10:11]
	global_load_dword v60, v[4:5], off nt
	global_load_dword v61, v[8:9], off nt
	global_load_dword v62, v[6:7], off nt
	global_load_dword v63, v[10:11], off nt
	v_lshlrev_b64 v[6:7], 8, v[0:1]
	v_add_u32_e32 v0, s0, v53
	v_mov_b32_e32 v29, v1
	v_mov_b32_e32 v31, v1
	v_add_u32_e32 v28, s5, v52
	v_add_u32_e32 v30, s5, v54
	v_lshlrev_b64 v[12:13], 8, v[12:13]
	v_lshlrev_b64 v[26:27], 8, v[26:27]
	v_lshl_add_u64 v[4:5], v[2:3], 0, v[32:33]
	v_lshl_add_u64 v[6:7], v[2:3], 0, v[6:7]
	v_lshlrev_b64 v[8:9], 8, v[0:1]
	v_add_u32_e32 v0, s0, v55
	v_lshlrev_b64 v[28:29], 8, v[28:29]
	v_lshlrev_b64 v[30:31], 8, v[30:31]
	v_lshl_add_u64 v[12:13], v[2:3], 0, v[12:13]
	v_lshl_add_u64 v[26:27], v[2:3], 0, v[26:27]
	global_load_dword v64, v[4:5], off nt
	global_load_dword v65, v[12:13], off nt
	global_load_dword v66, v[6:7], off nt
	global_load_dword v67, v[26:27], off nt
	v_lshl_add_u64 v[4:5], v[2:3], 0, v[8:9]
	v_lshlrev_b64 v[6:7], 8, v[0:1]
	v_lshl_add_u64 v[28:29], v[2:3], 0, v[28:29]
	v_lshl_add_u64 v[30:31], v[2:3], 0, v[30:31]
	v_lshl_add_u64 v[6:7], v[2:3], 0, v[6:7]
	global_load_dword v0, v[4:5], off nt
	global_load_dword v68, v[28:29], off nt
	global_load_dword v69, v[6:7], off nt
	global_load_dword v70, v[30:31], off nt
	s_add_i32 s8, s8, 16
	s_add_i32 s7, s7, 16
	s_add_i32 s4, s4, -16
	v_mad_u64_u32 v[4:5], s[10:11], v41, s26, v[18:19]
	s_cmp_lg_u32 s4, 0
	v_mad_u64_u32 v[6:7], s[10:11], v40, s26, v[18:19]
	v_mad_u64_u32 v[8:9], s[10:11], v43, s26, v[18:19]
	v_mad_u64_u32 v[10:11], s[10:11], v42, s26, v[18:19]
	v_mad_u64_u32 v[12:13], s[10:11], v45, s26, v[18:19]
	v_mad_u64_u32 v[26:27], s[10:11], v44, s26, v[18:19]
	v_mad_u64_u32 v[28:29], s[10:11], v47, s26, v[18:19]
	v_mad_u64_u32 v[30:31], s[10:11], v46, s26, v[18:19]
	v_mad_u64_u32 v[32:33], s[10:11], v49, s26, v[18:19]
	v_mad_u64_u32 v[34:35], s[10:11], v48, s26, v[18:19]
	v_mad_u64_u32 v[36:37], s[10:11], v51, s26, v[18:19]
	v_mad_u64_u32 v[40:41], s[10:11], v50, s26, v[18:19]
	v_mad_u64_u32 v[42:43], s[10:11], v53, s26, v[18:19]
	v_mad_u64_u32 v[44:45], s[10:11], v52, s26, v[18:19]
	v_mad_u64_u32 v[46:47], s[10:11], v55, s26, v[18:19]
	v_mad_u64_u32 v[48:49], s[10:11], v54, s26, v[18:19]
	s_waitcnt vmcnt(15)
	ds_write_b32 v4, v56
	s_waitcnt vmcnt(14)
	ds_write_b32 v6, v57
	s_waitcnt vmcnt(13)
	ds_write_b32 v8, v58
	s_waitcnt vmcnt(12)
	ds_write_b32 v10, v59
	s_waitcnt vmcnt(11)
	ds_write_b32 v12, v60
	s_waitcnt vmcnt(10)
	ds_write_b32 v26, v61
	s_waitcnt vmcnt(9)
	ds_write_b32 v28, v62
	s_waitcnt vmcnt(8)
	ds_write_b32 v30, v63
	s_waitcnt vmcnt(7)
	ds_write_b32 v32, v64
	s_waitcnt vmcnt(6)
	ds_write_b32 v34, v65
	s_waitcnt vmcnt(5)
	ds_write_b32 v36, v66
	s_waitcnt vmcnt(4)
	ds_write_b32 v40, v67
	s_waitcnt vmcnt(3)
	ds_write_b32 v42, v0
	s_waitcnt vmcnt(2)
	ds_write_b32 v44, v68
	s_waitcnt vmcnt(1)
	ds_write_b32 v46, v69
	s_waitcnt vmcnt(0)
	ds_write_b32 v48, v70
	s_cbranch_scc1 .LBB0_1460
; #define LAS __attribute__((address_space(3)))
; __device__ __forceinline__ v4u pack8(const float (&f)[8]) { v4u w; w.x = cvt_pk_bf16(f[0], f[1]); w.y = cvt_pk_bf16(f[2], f[3]); w.z = cvt_pk_bf16(f[4], f[5]); w.w = cvt_pk_bf16(f[6], f[7]); return w; }
; __device__ __forceinline__ void tr_item(const float* __restrict__ W, int ldw, int k0, int n0, bf16* __restrict__ WT, int ldt, int drow, const float* __restrict__ mu, LAS float* scr, int lane, const float* __restrict__ gs = nullptr) {
;     ...
; #pragma unroll
;     for (int j = 0; j < 4; ++j) {
;         const int n = (lane >> 3) + 8 * j; const LAS float* s = scr + (8 * c) * 33 + n;
;         float f[8];
; #pragma unroll
;         for (int e = 0; e < 8; ++e) f[e] = s[e * 33];
;         bf16* dp = WT + (size_t)(drow + n) * ldt + k0 + 8 * c;
;         if (mu) {
;             float f1[8], f2[8];
; #pragma unroll
;             for (int e = 0; e < 8; ++e) { f1[e] = f[e] * (1.f - mv[e]); f2[e] = f[e] * mv[e]; }
;             *(v4u*)dp = pack8(f1); *(v4u*)(dp + 1024) = pack8(f2);
	s_mul_i32 s7, s94, 6
	s_mul_hi_u32 s4, s94, 0xe00000
	s_mul_i32 s5, s94, 0xe00000
	s_or_b32 s94, s7, 1
	s_add_u32 s7, s36, s5
	s_addc_u32 s8, s37, s4
	s_lshl_b64 s[4:5], s[94:95], 12
	s_or_b32 s1, s1, 0xc00
	s_add_u32 s4, s50, s4
	v_or_b32_e32 v0, s0, v20
	s_addc_u32 s5, s51, s5
	s_waitcnt lgkmcnt(0)
	v_lshlrev_b32_e32 v0, 2, v0
	global_load_dwordx4 v[2:5], v0, s[4:5]
	global_load_dwordx4 v[6:9], v0, s[4:5] offset:16
	ds_read2_b32 v[26:27], v19 offset0:33 offset1:41
	ds_read2_b32 v[28:29], v19 offset0:66 offset1:74
	ds_read2_b32 v[30:31], v19 offset0:99 offset1:107
	ds_read2_b32 v[32:33], v19 offset0:132 offset1:140
	ds_read2_b32 v[34:35], v19 offset0:165 offset1:173
	ds_read2_b32 v[36:37], v19 offset0:198 offset1:206
	ds_read2_b32 v[40:41], v19 offset0:231 offset1:239
	ds_read2_b32 v[42:43], v19 offset1:8
	s_lshl_b32 s0, s0, 1
	s_add_u32 s4, s7, s0
	v_lshlrev_b32_e32 v0, 1, v20
	v_or_b32_e32 v10, s1, v17
	s_addc_u32 s5, s8, 0
	v_or_b32_e32 v11, s1, v21
	v_lshl_add_u64 v[44:45], s[4:5], 0, v[0:1]
	v_lshlrev_b32_e32 v0, 12, v10
	v_lshl_add_u64 v[46:47], v[44:45], 0, v[0:1]
	v_lshlrev_b32_e32 v0, 12, v11
	v_lshl_add_u64 v[48:49], v[44:45], 0, v[0:1]
	s_waitcnt vmcnt(1)
	v_sub_f32_e32 v53, 1.0, v5
	v_sub_f32_e32 v50, 1.0, v2
	s_waitcnt lgkmcnt(0)
	v_mul_f32_e32 v0, v2, v42
	v_sub_f32_e32 v51, 1.0, v3
	v_mul_f32_e32 v10, v3, v26
	v_sub_f32_e32 v52, 1.0, v4
	v_mul_f32_e32 v11, v4, v28
	v_mul_f32_e32 v12, v5, v30
	s_waitcnt vmcnt(0)
	v_sub_f32_e32 v54, 1.0, v6
	v_mul_f32_e32 v13, v6, v32
	v_sub_f32_e32 v55, 1.0, v7
	v_mul_f32_e32 v56, v7, v34
	v_sub_f32_e32 v57, 1.0, v8
	v_sub_f32_e32 v59, 1.0, v9
	v_mul_f32_e32 v30, v53, v30
	v_mul_f32_e32 v58, v8, v36
	v_mul_f32_e32 v60, v9, v40
	v_mul_f32_e32 v61, v2, v43
	v_mul_f32_e32 v62, v3, v27
	v_mul_f32_e32 v63, v4, v29
	v_mul_f32_e32 v64, v5, v31
	v_mul_f32_e32 v42, v50, v42
	v_mul_f32_e32 v69, v51, v26
	v_mul_f32_e32 v70, v52, v28
	v_mul_f32_e32 v32, v54, v32
	v_mul_f32_e32 v34, v55, v34
	v_mul_f32_e32 v36, v57, v36
	v_mul_f32_e32 v40, v59, v40
	v_cvt_pk_bf16_f32 v10, v0, v10
	v_cvt_pk_bf16_f32 v11, v11, v12
	v_cvt_pk_bf16_f32 v12, v13, v56
	v_cvt_pk_bf16_f32 v13, v58, v60
	v_mul_f32_e32 v0, v50, v43
	v_mul_f32_e32 v27, v51, v27
	v_mul_f32_e32 v43, v52, v29
	v_mul_f32_e32 v56, v53, v31
	v_cvt_pk_bf16_f32 v28, v42, v69
	v_cvt_pk_bf16_f32 v29, v70, v30
	v_cvt_pk_bf16_f32 v30, v32, v34
	v_cvt_pk_bf16_f32 v31, v36, v40
	v_mul_f32_e32 v65, v6, v33
	v_mul_f32_e32 v66, v7, v35
	v_mul_f32_e32 v67, v8, v37
	v_mul_f32_e32 v68, v9, v41
	v_mul_f32_e32 v33, v54, v33
	v_mul_f32_e32 v35, v55, v35
	v_mul_f32_e32 v37, v57, v37
	v_mul_f32_e32 v41, v59, v41
	v_cvt_pk_bf16_f32 v26, v61, v62
	global_store_dwordx4 v[46:47], v[10:13], off offset:2048 sc1
	s_nop 1
	v_cvt_pk_bf16_f32 v10, v0, v27
	v_cvt_pk_bf16_f32 v11, v43, v56
	v_cvt_pk_bf16_f32 v12, v33, v35
	v_cvt_pk_bf16_f32 v13, v37, v41
	global_store_dwordx4 v[46:47], v[28:31], off sc1
	global_store_dwordx4 v[48:49], v[10:13], off sc1
	v_cvt_pk_bf16_f32 v27, v63, v64
	v_or_b32_e32 v0, s1, v38
	v_cvt_pk_bf16_f32 v28, v65, v66
	v_cvt_pk_bf16_f32 v29, v67, v68
	global_store_dwordx4 v[48:49], v[26:29], off offset:2048 sc1
	ds_read2_b32 v[26:27], v19 offset0:16 offset1:24
	ds_read2_b32 v[28:29], v19 offset0:49 offset1:57
	ds_read2_b32 v[30:31], v19 offset0:82 offset1:90
	ds_read2_b32 v[32:33], v19 offset0:115 offset1:123
	ds_read2_b32 v[34:35], v19 offset0:148 offset1:156
	ds_read2_b32 v[36:37], v19 offset0:181 offset1:189
	ds_read2_b32 v[40:41], v19 offset0:214 offset1:222
	ds_read2_b32 v[42:43], v19 offset0:247 offset1:255
	v_lshlrev_b32_e32 v0, 12, v0
	v_lshl_add_u64 v[46:47], v[44:45], 0, v[0:1]
	s_waitcnt lgkmcnt(7)
	v_mul_f32_e32 v0, v50, v26
	s_waitcnt lgkmcnt(6)
	v_mul_f32_e32 v10, v51, v28
	s_waitcnt lgkmcnt(5)
	v_mul_f32_e32 v11, v52, v30
	s_waitcnt lgkmcnt(4)
	v_mul_f32_e32 v12, v53, v32
	s_waitcnt lgkmcnt(3)
	v_mul_f32_e32 v13, v54, v34
	s_waitcnt lgkmcnt(2)
	v_mul_f32_e32 v48, v55, v36
	s_waitcnt lgkmcnt(1)
	v_mul_f32_e32 v49, v57, v40
	s_waitcnt lgkmcnt(0)
	v_mul_f32_e32 v56, v59, v42
	v_cvt_pk_bf16_f32 v10, v0, v10
	v_cvt_pk_bf16_f32 v11, v11, v12
	v_cvt_pk_bf16_f32 v12, v13, v48
	v_cvt_pk_bf16_f32 v13, v49, v56
	v_or_b32_e32 v0, s1, v39
	v_mul_f32_e32 v26, v2, v26
	v_mul_f32_e32 v28, v3, v28
	v_mul_f32_e32 v30, v4, v30
	v_mul_f32_e32 v32, v5, v32
	v_mul_f32_e32 v34, v6, v34
	v_mul_f32_e32 v36, v7, v36
	v_mul_f32_e32 v40, v8, v40
	v_mul_f32_e32 v42, v9, v42
	global_store_dwordx4 v[46:47], v[10:13], off sc1
	v_lshlrev_b32_e32 v0, 12, v0
	v_mul_f32_e32 v6, v6, v35
	v_cvt_pk_bf16_f32 v10, v26, v28
	v_cvt_pk_bf16_f32 v11, v30, v32
	v_cvt_pk_bf16_f32 v12, v34, v36
	v_cvt_pk_bf16_f32 v13, v40, v42
	global_store_dwordx4 v[46:47], v[10:13], off offset:2048 sc1
	v_mul_f32_e32 v26, v4, v31
	v_mul_f32_e32 v4, v53, v33
	v_lshl_add_u64 v[10:11], v[44:45], 0, v[0:1]
	v_mul_f32_e32 v0, v50, v27
	v_mul_f32_e32 v12, v2, v27
	v_mul_f32_e32 v2, v51, v29
	v_mul_f32_e32 v13, v3, v29
	v_mul_f32_e32 v3, v52, v31
	v_mul_f32_e32 v27, v5, v33
	v_mul_f32_e32 v5, v54, v35
	v_mul_f32_e32 v28, v55, v37
	v_mul_f32_e32 v29, v57, v41
	v_mul_f32_e32 v30, v59, v43
	v_cvt_pk_bf16_f32 v2, v0, v2
	v_cvt_pk_bf16_f32 v3, v3, v4
	v_cvt_pk_bf16_f32 v4, v5, v28
	v_cvt_pk_bf16_f32 v5, v29, v30
	v_mul_f32_e32 v7, v7, v37
	v_mul_f32_e32 v8, v8, v41
	v_mul_f32_e32 v9, v9, v43
	global_store_dwordx4 v[10:11], v[2:5], off sc1
	s_nop 1
	v_cvt_pk_bf16_f32 v2, v12, v13
	v_cvt_pk_bf16_f32 v3, v26, v27
	v_cvt_pk_bf16_f32 v4, v6, v7
	v_cvt_pk_bf16_f32 v5, v8, v9
	global_store_dwordx4 v[10:11], v[2:5], off offset:2048 sc1
	s_waitcnt lgkmcnt(0)

; #define LAS __attribute__((address_space(3)))
; __device__ __forceinline__ v4u pack8(const float (&f)[8]) { v4u w; w.x = cvt_pk_bf16(f[0], f[1]); w.y = cvt_pk_bf16(f[2], f[3]); w.z = cvt_pk_bf16(f[4], f[5]); w.w = cvt_pk_bf16(f[6], f[7]); return w; }
; __device__ __forceinline__ void tr_item(const float* __restrict__ W, int ldw, int k0, int n0, bf16* __restrict__ WT, int ldt, int drow, const float* __restrict__ mu, LAS float* scr, int lane, const float* __restrict__ gs = nullptr) {
;     ...
; #pragma unroll
;     for (int j = 0; j < 4; ++j) {
;         const int n = (lane >> 3) + 8 * j; const LAS float* s = scr + (8 * c) * 33 + n;
;         float f[8];
; #pragma unroll
;         for (int e = 0; e < 8; ++e) f[e] = s[e * 33];
;         bf16* dp = WT + (size_t)(drow + n) * ldt + k0 + 8 * c;
;         if (mu) {
;             float f1[8], f2[8];
; #pragma unroll
;             for (int e = 0; e < 8; ++e) { f1[e] = f[e] * (1.f - mv[e]); f2[e] = f[e] * mv[e]; }
;             *(v4u*)dp = pack8(f1); *(v4u*)(dp + 1024) = pack8(f2);
.LBB0_1470:
	s_and_b64 s[4:5], s[4:5], exec
	s_cselect_b32 s4, 0xe00000, 0
	s_lshl_b32 s5, s7, 10
	s_add_u32 s4, s36, s4
	ds_read2_b32 v[36:37], v19 offset1:33
	ds_read2_b32 v[34:35], v19 offset0:66 offset1:99
	ds_read2_b32 v[32:33], v19 offset0:132 offset1:165
	ds_read2_b32 v[30:31], v19 offset0:198 offset1:231
	s_addc_u32 s10, s37, 0
	s_or_b32 s7, s5, s9
	s_lshl_b32 s5, s8, 1
	s_add_u32 s4, s4, s5
	s_addc_u32 s5, s10, 0
	v_lshlrev_b32_e32 v0, 1, v20
	v_lshl_add_u64 v[26:27], s[4:5], 0, v[0:1]
	v_or_b32_e32 v0, s7, v17
	v_lshlrev_b64 v[10:11], 12, v[0:1]
	v_lshl_add_u64 v[28:29], v[26:27], 0, v[10:11]
	s_and_b64 vcc, exec, s[0:1]
	s_waitcnt vmcnt(1)
	v_sub_f32_e32 v47, 1.0, v2
	v_sub_f32_e32 v46, 1.0, v3
	v_sub_f32_e32 v45, 1.0, v4
	v_sub_f32_e32 v44, 1.0, v5
	s_waitcnt vmcnt(0)
	v_sub_f32_e32 v43, 1.0, v6
	v_sub_f32_e32 v42, 1.0, v7
	v_sub_f32_e32 v40, 1.0, v8
	v_sub_f32_e32 v41, 1.0, v9
	s_cbranch_vccnz .LBB0_1493
	s_waitcnt lgkmcnt(3)
	v_mul_f32_e32 v48, v36, v2
	v_mul_f32_e32 v10, v37, v46
	v_mul_f32_e32 v49, v3, v37
	s_waitcnt lgkmcnt(2)
	v_mul_f32_e32 v11, v45, v34
	v_mul_f32_e32 v50, v4, v34
	v_mul_f32_e32 v12, v44, v35
	v_mul_f32_e32 v51, v5, v35
	s_waitcnt lgkmcnt(1)
	v_mul_f32_e32 v13, v43, v32
	v_mul_f32_e32 v0, v36, v47
	v_mul_f32_e32 v52, v6, v32
	v_mul_f32_e32 v53, v42, v33
	v_mul_f32_e32 v54, v7, v33
	s_waitcnt lgkmcnt(0)
	v_mul_f32_e32 v55, v40, v30
	v_mul_f32_e32 v56, v8, v30
	v_mul_f32_e32 v57, v41, v31
	v_mul_f32_e32 v58, v9, v31
	v_cvt_pk_bf16_f32 v10, v0, v10
	v_cvt_pk_bf16_f32 v11, v11, v12
	v_cvt_pk_bf16_f32 v12, v13, v53
	v_cvt_pk_bf16_f32 v13, v55, v57
	v_cvt_pk_bf16_f32 v48, v48, v49
	v_cvt_pk_bf16_f32 v49, v50, v51
	v_cvt_pk_bf16_f32 v50, v52, v54
	v_cvt_pk_bf16_f32 v51, v56, v58
	global_store_dwordx4 v[28:29], v[48:51], off offset:2048 sc1
	s_cbranch_execnz .LBB0_1473

; #define LAS __attribute__((address_space(3)))
; __device__ __forceinline__ v4u pack8(const float (&f)[8]) { v4u w; w.x = cvt_pk_bf16(f[0], f[1]); w.y = cvt_pk_bf16(f[2], f[3]); w.z = cvt_pk_bf16(f[4], f[5]); w.w = cvt_pk_bf16(f[6], f[7]); return w; }
; __device__ __forceinline__ void tr_item(const float* __restrict__ W, int ldw, int k0, int n0, bf16* __restrict__ WT, int ldt, int drow, const float* __restrict__ mu, LAS float* scr, int lane, const float* __restrict__ gs = nullptr) {
;     ...
; #pragma unroll
;     for (int j = 0; j < 4; ++j) {
;         const int n = (lane >> 3) + 8 * j; const LAS float* s = scr + (8 * c) * 33 + n;
;         float f[8];
; #pragma unroll
;         for (int e = 0; e < 8; ++e) f[e] = s[e * 33];
;         bf16* dp = WT + (size_t)(drow + n) * ldt + k0 + 8 * c;
;         if (mu) {
;             float f1[8], f2[8];
; #pragma unroll
;             for (int e = 0; e < 8; ++e) { f1[e] = f[e] * (1.f - mv[e]); f2[e] = f[e] * mv[e]; }
;             *(v4u*)dp = pack8(f1); *(v4u*)(dp + 1024) = pack8(f2);
.LBB0_1473:
	global_store_dwordx4 v[28:29], v[10:13], off sc1
	s_waitcnt lgkmcnt(3)
	ds_read2_b32 v[36:37], v19 offset0:8 offset1:41
	s_waitcnt lgkmcnt(3)
	ds_read2_b32 v[34:35], v19 offset0:74 offset1:107
	s_waitcnt lgkmcnt(3)
	ds_read2_b32 v[32:33], v19 offset0:140 offset1:173
	s_waitcnt lgkmcnt(3)
	ds_read2_b32 v[30:31], v19 offset0:206 offset1:239
	v_or_b32_e32 v0, s7, v21
	v_lshlrev_b64 v[10:11], 12, v[0:1]
	s_and_b64 vcc, exec, s[0:1]
	v_lshl_add_u64 v[28:29], v[26:27], 0, v[10:11]
	s_cbranch_vccnz .LBB0_1494
	s_waitcnt lgkmcnt(3)
	v_mul_f32_e32 v48, v2, v36
	v_mul_f32_e32 v10, v46, v37
	v_mul_f32_e32 v49, v3, v37
	s_waitcnt lgkmcnt(2)
	v_mul_f32_e32 v11, v45, v34
	v_mul_f32_e32 v50, v4, v34
	v_mul_f32_e32 v12, v44, v35
	v_mul_f32_e32 v51, v5, v35
	s_waitcnt lgkmcnt(1)
	v_mul_f32_e32 v13, v43, v32
	v_mul_f32_e32 v0, v47, v36
	v_mul_f32_e32 v52, v6, v32
	v_mul_f32_e32 v53, v42, v33
	v_mul_f32_e32 v54, v7, v33
	s_waitcnt lgkmcnt(0)
	v_mul_f32_e32 v55, v40, v30
	v_mul_f32_e32 v56, v8, v30
	v_mul_f32_e32 v57, v41, v31
	v_mul_f32_e32 v58, v9, v31
	v_cvt_pk_bf16_f32 v10, v0, v10
	v_cvt_pk_bf16_f32 v11, v11, v12
	v_cvt_pk_bf16_f32 v12, v13, v53
	v_cvt_pk_bf16_f32 v13, v55, v57
	v_cvt_pk_bf16_f32 v48, v48, v49
	v_cvt_pk_bf16_f32 v49, v50, v51
	v_cvt_pk_bf16_f32 v50, v52, v54
	v_cvt_pk_bf16_f32 v51, v56, v58
	global_store_dwordx4 v[28:29], v[48:51], off offset:2048 sc1
	s_cbranch_execnz .LBB0_1476

; #define LAS __attribute__((address_space(3)))
; __device__ __forceinline__ v4u pack8(const float (&f)[8]) { v4u w; w.x = cvt_pk_bf16(f[0], f[1]); w.y = cvt_pk_bf16(f[2], f[3]); w.z = cvt_pk_bf16(f[4], f[5]); w.w = cvt_pk_bf16(f[6], f[7]); return w; }
; __device__ __forceinline__ void tr_item(const float* __restrict__ W, int ldw, int k0, int n0, bf16* __restrict__ WT, int ldt, int drow, const float* __restrict__ mu, LAS float* scr, int lane, const float* __restrict__ gs = nullptr) {
;     ...
; #pragma unroll
;     for (int j = 0; j < 4; ++j) {
;         const int n = (lane >> 3) + 8 * j; const LAS float* s = scr + (8 * c) * 33 + n;
;         float f[8];
; #pragma unroll
;         for (int e = 0; e < 8; ++e) f[e] = s[e * 33];
;         bf16* dp = WT + (size_t)(drow + n) * ldt + k0 + 8 * c;
;         if (mu) {
;             float f1[8], f2[8];
; #pragma unroll
;             for (int e = 0; e < 8; ++e) { f1[e] = f[e] * (1.f - mv[e]); f2[e] = f[e] * mv[e]; }
;             *(v4u*)dp = pack8(f1); *(v4u*)(dp + 1024) = pack8(f2);
.LBB0_1476:
	global_store_dwordx4 v[28:29], v[10:13], off sc1
	s_waitcnt lgkmcnt(3)
	ds_read2_b32 v[36:37], v19 offset0:16 offset1:49
	s_waitcnt lgkmcnt(3)
	ds_read2_b32 v[34:35], v19 offset0:82 offset1:115
	s_waitcnt lgkmcnt(3)
	ds_read2_b32 v[32:33], v19 offset0:148 offset1:181
	s_waitcnt lgkmcnt(3)
	ds_read2_b32 v[30:31], v19 offset0:214 offset1:247
	v_or_b32_e32 v0, s7, v38
	v_lshlrev_b64 v[10:11], 12, v[0:1]
	s_and_b64 vcc, exec, s[0:1]
	v_lshl_add_u64 v[28:29], v[26:27], 0, v[10:11]
	s_cbranch_vccnz .LBB0_1495
	s_waitcnt lgkmcnt(3)
	v_mul_f32_e32 v48, v2, v36
	v_mul_f32_e32 v10, v46, v37
	v_mul_f32_e32 v49, v3, v37
	s_waitcnt lgkmcnt(2)
	v_mul_f32_e32 v11, v45, v34
	v_mul_f32_e32 v50, v4, v34
	v_mul_f32_e32 v12, v44, v35
	v_mul_f32_e32 v51, v5, v35
	s_waitcnt lgkmcnt(1)
	v_mul_f32_e32 v13, v43, v32
	v_mul_f32_e32 v0, v47, v36
	v_mul_f32_e32 v52, v6, v32
	v_mul_f32_e32 v53, v42, v33
	v_mul_f32_e32 v54, v7, v33
	s_waitcnt lgkmcnt(0)
	v_mul_f32_e32 v55, v40, v30
	v_mul_f32_e32 v56, v8, v30
	v_mul_f32_e32 v57, v41, v31
	v_mul_f32_e32 v58, v9, v31
	v_cvt_pk_bf16_f32 v10, v0, v10
	v_cvt_pk_bf16_f32 v11, v11, v12
	v_cvt_pk_bf16_f32 v12, v13, v53
	v_cvt_pk_bf16_f32 v13, v55, v57
	v_cvt_pk_bf16_f32 v48, v48, v49
	v_cvt_pk_bf16_f32 v49, v50, v51
	v_cvt_pk_bf16_f32 v50, v52, v54
	v_cvt_pk_bf16_f32 v51, v56, v58
	global_store_dwordx4 v[28:29], v[48:51], off offset:2048 sc1
	s_cbranch_execnz .LBB0_1479

; #define LAS __attribute__((address_space(3)))
; __device__ __forceinline__ v4u pack8(const float (&f)[8]) { v4u w; w.x = cvt_pk_bf16(f[0], f[1]); w.y = cvt_pk_bf16(f[2], f[3]); w.z = cvt_pk_bf16(f[4], f[5]); w.w = cvt_pk_bf16(f[6], f[7]); return w; }
; __device__ __forceinline__ void tr_item(const float* __restrict__ W, int ldw, int k0, int n0, bf16* __restrict__ WT, int ldt, int drow, const float* __restrict__ mu, LAS float* scr, int lane, const float* __restrict__ gs = nullptr) {
;     ...
; #pragma unroll
;     for (int j = 0; j < 4; ++j) {
;         const int n = (lane >> 3) + 8 * j; const LAS float* s = scr + (8 * c) * 33 + n;
;         float f[8];
; #pragma unroll
;         for (int e = 0; e < 8; ++e) f[e] = s[e * 33];
;         bf16* dp = WT + (size_t)(drow + n) * ldt + k0 + 8 * c;
;         if (mu) {
;             float f1[8], f2[8];
; #pragma unroll
;             for (int e = 0; e < 8; ++e) { f1[e] = f[e] * (1.f - mv[e]); f2[e] = f[e] * mv[e]; }
;             *(v4u*)dp = pack8(f1); *(v4u*)(dp + 1024) = pack8(f2);
.LBB0_1479:
	global_store_dwordx4 v[28:29], v[10:13], off sc1
	s_waitcnt lgkmcnt(1)
	ds_read2_b32 v[32:33], v19 offset0:24 offset1:57
	s_waitcnt lgkmcnt(1)
	ds_read2_b32 v[30:31], v19 offset0:90 offset1:123
	ds_read2_b32 v[28:29], v19 offset0:156 offset1:189
	ds_read2_b32 v[12:13], v19 offset0:222 offset1:255
	v_or_b32_e32 v0, s7, v39
	v_lshlrev_b64 v[10:11], 12, v[0:1]
	s_and_b64 vcc, exec, s[0:1]
	v_lshl_add_u64 v[10:11], v[26:27], 0, v[10:11]
	s_cbranch_vccnz .LBB0_1496
	s_waitcnt lgkmcnt(3)
	v_mul_f32_e32 v26, v2, v32
	v_mul_f32_e32 v2, v46, v33
	v_mul_f32_e32 v27, v3, v33
	s_waitcnt lgkmcnt(2)
	v_mul_f32_e32 v3, v45, v30
	v_mul_f32_e32 v34, v4, v30
	v_mul_f32_e32 v4, v44, v31
	v_mul_f32_e32 v35, v5, v31
	s_waitcnt lgkmcnt(1)
	v_mul_f32_e32 v5, v43, v28
	v_mul_f32_e32 v36, v6, v28
	v_mul_f32_e32 v6, v42, v29
	v_mul_f32_e32 v37, v7, v29
	s_waitcnt lgkmcnt(0)
	v_mul_f32_e32 v7, v40, v12
	v_mul_f32_e32 v40, v8, v12
	v_mul_f32_e32 v8, v41, v13
	v_mul_f32_e32 v9, v9, v13
	v_mul_f32_e32 v0, v47, v32
	v_cvt_pk_bf16_f32 v2, v0, v2
	v_cvt_pk_bf16_f32 v3, v3, v4
	v_cvt_pk_bf16_f32 v4, v5, v6
	v_cvt_pk_bf16_f32 v5, v7, v8
	v_cvt_pk_bf16_f32 v6, v26, v27
	v_cvt_pk_bf16_f32 v7, v34, v35
	v_cvt_pk_bf16_f32 v8, v36, v37
	v_cvt_pk_bf16_f32 v9, v40, v9
	global_store_dwordx4 v[10:11], v[6:9], off offset:2048 sc1
	s_cbranch_execnz .LBB0_1482

; __device__ __forceinline__ v4u pack8(const float (&f)[8]) { v4u w; w.x = cvt_pk_bf16(f[0], f[1]); w.y = cvt_pk_bf16(f[2], f[3]); w.z = cvt_pk_bf16(f[4], f[5]); w.w = cvt_pk_bf16(f[6], f[7]); return w; }
; __device__ __forceinline__ void tr_item(const float* __restrict__ W, int ldw, int k0, int n0, bf16* __restrict__ WT, int ldt, int drow, const float* __restrict__ mu, LAS float* scr, int lane, const float* __restrict__ gs = nullptr) {
;     ...
;             for (int e = 0; e < 8; ++e) { f1[e] = f[e] * (1.f - mv[e]); f2[e] = f[e] * mv[e]; }
;             *(v4u*)dp = pack8(f1); *(v4u*)(dp + 1024) = pack8(f2);
.LBB0_1482:
	global_store_dwordx4 v[10:11], v[2:5], off sc1
	s_waitcnt lgkmcnt(0)

; __device__ __forceinline__ void tr_item(const float* __restrict__ W, int ldw, int k0, int n0, bf16* __restrict__ WT, int ldt, int drow, const float* __restrict__ mu, LAS float* scr, int lane, const float* __restrict__ gs = nullptr) {
; #pragma unroll 8
;     for (int i = 0; i < 32; ++i) { const int kk = 2 * i + (lane >> 5); scr[kk * 33 + (lane & 31)] = W[(size_t)(k0 + kk) * ldw + n0 + (lane & 31)]; }
;     asm volatile("s_waitcnt lgkmcnt(0)" ::: "memory");
.LBB0_1486:
	s_lshl_b32 s9, s4, 1
	s_lshl_b32 s10, s7, 1
	v_or_b32_e32 v41, s10, v14
	s_add_i32 s11, s9, 4
	s_add_i32 s12, s10, 4
	s_add_i32 s14, s10, 8
	v_add_u32_e32 v0, s1, v41
	v_or_b32_e32 v42, s11, v15
	v_or_b32_e32 v43, s12, v14
	v_mov_b32_e32 v7, v1
	v_or_b32_e32 v40, s9, v15
	s_add_i32 s16, s10, 12
	v_or_b32_e32 v45, s14, v14
	s_waitcnt lgkmcnt(3)
	v_lshlrev_b64 v[32:33], 12, v[0:1]
	v_add_u32_e32 v6, s5, v42
	v_add_u32_e32 v0, s1, v43
	v_mov_b32_e32 v5, v1
	s_add_i32 s13, s9, 8
	s_add_i32 s15, s9, 12
	s_add_i32 s18, s10, 16
	v_add_u32_e32 v4, s5, v40
	v_or_b32_e32 v47, s16, v14
	v_lshlrev_b64 v[6:7], 12, v[6:7]
	v_lshlrev_b64 v[34:35], 12, v[0:1]
	v_add_u32_e32 v0, s1, v45
	s_add_i32 s20, s10, 20
	v_or_b32_e32 v44, s13, v15
	v_or_b32_e32 v46, s15, v15
	v_or_b32_e32 v49, s18, v14
	v_lshlrev_b64 v[4:5], 12, v[4:5]
	v_lshl_add_u64 v[32:33], v[2:3], 0, v[32:33]
	v_lshl_add_u64 v[6:7], v[2:3], 0, v[6:7]
	v_lshlrev_b64 v[36:37], 12, v[0:1]
	v_add_u32_e32 v0, s1, v47
	v_mov_b32_e32 v9, v1
	v_mov_b32_e32 v11, v1
	s_add_i32 s17, s9, 16
	s_add_i32 s19, s9, 20
	s_add_i32 s22, s10, 24
	v_or_b32_e32 v51, s20, v14
	v_add_u32_e32 v8, s5, v44
	v_add_u32_e32 v10, s5, v46
	v_lshl_add_u64 v[4:5], v[2:3], 0, v[4:5]
	v_lshl_add_u64 v[34:35], v[2:3], 0, v[34:35]
	global_load_dword v56, v[32:33], off nt
	global_load_dword v57, v[4:5], off nt
	global_load_dword v58, v[34:35], off nt
	global_load_dword v59, v[6:7], off nt
	v_lshlrev_b64 v[6:7], 12, v[0:1]
	v_add_u32_e32 v0, s1, v49
	s_add_i32 s21, s9, 24
	s_add_i32 s9, s9, 28
	s_add_i32 s10, s10, 28
	v_or_b32_e32 v48, s17, v15
	v_or_b32_e32 v50, s19, v15
	v_or_b32_e32 v53, s22, v14
	v_lshlrev_b64 v[8:9], 12, v[8:9]
	v_lshlrev_b64 v[10:11], 12, v[10:11]
	v_lshl_add_u64 v[4:5], v[2:3], 0, v[36:37]
	v_lshl_add_u64 v[6:7], v[2:3], 0, v[6:7]
	v_lshlrev_b64 v[32:33], 12, v[0:1]
	v_add_u32_e32 v0, s1, v51
	s_waitcnt lgkmcnt(0)
	v_mov_b32_e32 v13, v1
	v_mov_b32_e32 v27, v1
	v_or_b32_e32 v52, s21, v15
	v_or_b32_e32 v54, s9, v15
	v_or_b32_e32 v55, s10, v14
	v_add_u32_e32 v12, s5, v48
	v_add_u32_e32 v26, s5, v50
	v_lshl_add_u64 v[8:9], v[2:3], 0, v[8:9]
	v_lshl_add_u64 v[10:11], v[2:3], 0, v[10:11]
	global_load_dword v60, v[4:5], off nt
	global_load_dword v61, v[8:9], off nt
	global_load_dword v62, v[6:7], off nt
	global_load_dword v63, v[10:11], off nt
	v_lshlrev_b64 v[6:7], 12, v[0:1]
	v_add_u32_e32 v0, s1, v53
	v_mov_b32_e32 v29, v1
	v_mov_b32_e32 v31, v1
	v_add_u32_e32 v28, s5, v52
	v_add_u32_e32 v30, s5, v54
	v_lshlrev_b64 v[12:13], 12, v[12:13]
	v_lshlrev_b64 v[26:27], 12, v[26:27]
	v_lshl_add_u64 v[4:5], v[2:3], 0, v[32:33]
	v_lshl_add_u64 v[6:7], v[2:3], 0, v[6:7]
	v_lshlrev_b64 v[8:9], 12, v[0:1]
	v_add_u32_e32 v0, s1, v55
	v_lshlrev_b64 v[28:29], 12, v[28:29]
	v_lshlrev_b64 v[30:31], 12, v[30:31]
	v_lshl_add_u64 v[12:13], v[2:3], 0, v[12:13]
	v_lshl_add_u64 v[26:27], v[2:3], 0, v[26:27]
	global_load_dword v64, v[4:5], off nt
	global_load_dword v65, v[12:13], off nt
	global_load_dword v66, v[6:7], off nt
	global_load_dword v67, v[26:27], off nt
	v_lshl_add_u64 v[4:5], v[2:3], 0, v[8:9]
	v_lshlrev_b64 v[6:7], 12, v[0:1]
	v_lshl_add_u64 v[28:29], v[2:3], 0, v[28:29]
	v_lshl_add_u64 v[30:31], v[2:3], 0, v[30:31]
	v_lshl_add_u64 v[6:7], v[2:3], 0, v[6:7]
	global_load_dword v0, v[4:5], off nt
	global_load_dword v68, v[28:29], off nt
	global_load_dword v69, v[6:7], off nt
	global_load_dword v70, v[30:31], off nt
	s_add_i32 s7, s7, 16
	s_add_i32 s4, s4, 16
	s_add_i32 s8, s8, -16
	v_mad_u64_u32 v[4:5], s[10:11], v41, s26, v[18:19]
	s_cmp_lg_u32 s8, 0
	v_mad_u64_u32 v[6:7], s[10:11], v40, s26, v[18:19]
	v_mad_u64_u32 v[8:9], s[10:11], v43, s26, v[18:19]
	v_mad_u64_u32 v[10:11], s[10:11], v42, s26, v[18:19]
	v_mad_u64_u32 v[12:13], s[10:11], v45, s26, v[18:19]
	v_mad_u64_u32 v[26:27], s[10:11], v44, s26, v[18:19]
	v_mad_u64_u32 v[28:29], s[10:11], v47, s26, v[18:19]
	v_mad_u64_u32 v[30:31], s[10:11], v46, s26, v[18:19]
	v_mad_u64_u32 v[32:33], s[10:11], v49, s26, v[18:19]
	v_mad_u64_u32 v[34:35], s[10:11], v48, s26, v[18:19]
	v_mad_u64_u32 v[36:37], s[10:11], v51, s26, v[18:19]
	v_mad_u64_u32 v[40:41], s[10:11], v50, s26, v[18:19]
	v_mad_u64_u32 v[42:43], s[10:11], v53, s26, v[18:19]
	v_mad_u64_u32 v[44:45], s[10:11], v52, s26, v[18:19]
	v_mad_u64_u32 v[46:47], s[10:11], v55, s26, v[18:19]
	v_mad_u64_u32 v[48:49], s[10:11], v54, s26, v[18:19]
	s_waitcnt vmcnt(15)
	ds_write_b32 v4, v56
	s_waitcnt vmcnt(14)
	ds_write_b32 v6, v57
	s_waitcnt vmcnt(13)
	ds_write_b32 v8, v58
	s_waitcnt vmcnt(12)
	ds_write_b32 v10, v59
	s_waitcnt vmcnt(11)
	ds_write_b32 v12, v60
	s_waitcnt vmcnt(10)
	ds_write_b32 v26, v61
	s_waitcnt vmcnt(9)
	ds_write_b32 v28, v62
	s_waitcnt vmcnt(8)
	ds_write_b32 v30, v63
	s_waitcnt vmcnt(7)
	ds_write_b32 v32, v64
	s_waitcnt vmcnt(6)
	ds_write_b32 v34, v65
	s_waitcnt vmcnt(5)
	ds_write_b32 v36, v66
	s_waitcnt vmcnt(4)
	ds_write_b32 v40, v67
	s_waitcnt vmcnt(3)
	ds_write_b32 v42, v0
	s_waitcnt vmcnt(2)
	ds_write_b32 v44, v68
	s_waitcnt vmcnt(1)
	ds_write_b32 v46, v69
	s_waitcnt vmcnt(0)
	ds_write_b32 v48, v70
	s_cbranch_scc1 .LBB0_1486
; __device__ __forceinline__ v4u pack8(const float (&f)[8]) { v4u w; w.x = cvt_pk_bf16(f[0], f[1]); w.y = cvt_pk_bf16(f[2], f[3]); w.z = cvt_pk_bf16(f[4], f[5]); w.w = cvt_pk_bf16(f[6], f[7]); return w; }
; __device__ __forceinline__ void tr_item(const float* __restrict__ W, int ldw, int k0, int n0, bf16* __restrict__ WT, int ldt, int drow, const float* __restrict__ mu, LAS float* scr, int lane, const float* __restrict__ gs = nullptr) {
;     ...
;         for (int e = 0; e < 8; ++e) f[e] = s[e * 33];
;     ...
;         } else { if (gs) {
; #pragma unroll
;             for (int e = 0; e < 8; ++e) f[e] *= mv[e]; }
;             *(v4u*)dp = pack8(f); }
	s_lshl_b64 s[4:5], s[94:95], 22
	v_readlane_b32 s7, v252, 20
	s_add_u32 s4, s7, s4
	v_readlane_b32 s7, v252, 21
	s_addc_u32 s5, s7, s5
	s_lshl_b32 s1, s1, 1
	s_waitcnt lgkmcnt(0)
	s_add_u32 s4, s4, s1
	s_addc_u32 s5, s5, 0
	v_lshlrev_b32_e32 v0, 1, v20
	ds_read2_b32 v[8:9], v19 offset0:33 offset1:41
	ds_read2_b32 v[10:11], v19 offset1:8
	ds_read2_b32 v[12:13], v19 offset0:66 offset1:74
	ds_read2_b32 v[26:27], v19 offset0:99 offset1:107
	ds_read2_b32 v[28:29], v19 offset0:132 offset1:140
	ds_read2_b32 v[30:31], v19 offset0:165 offset1:173
	ds_read2_b32 v[32:33], v19 offset0:198 offset1:206
	ds_read2_b32 v[34:35], v19 offset0:231 offset1:239
	v_lshl_add_u64 v[6:7], s[4:5], 0, v[0:1]
	v_or_b32_e32 v0, s0, v17
	v_lshlrev_b32_e32 v0, 12, v0
	v_lshl_add_u64 v[36:37], v[6:7], 0, v[0:1]
	v_or_b32_e32 v0, s0, v21
	v_lshlrev_b32_e32 v0, 12, v0
	s_waitcnt lgkmcnt(6)
	v_cvt_pk_bf16_f32 v2, v10, v8
	s_waitcnt lgkmcnt(4)
	v_cvt_pk_bf16_f32 v3, v12, v26
	s_waitcnt lgkmcnt(2)
	v_cvt_pk_bf16_f32 v4, v28, v30
	s_waitcnt lgkmcnt(0)
	v_cvt_pk_bf16_f32 v5, v32, v34
	global_store_dwordx4 v[36:37], v[2:5], off sc1
	v_lshl_add_u64 v[36:37], v[6:7], 0, v[0:1]
	v_or_b32_e32 v0, s0, v38
	v_cvt_pk_bf16_f32 v2, v11, v9
	v_cvt_pk_bf16_f32 v3, v13, v27
	v_cvt_pk_bf16_f32 v4, v29, v31
	v_cvt_pk_bf16_f32 v5, v33, v35
	global_store_dwordx4 v[36:37], v[2:5], off sc1
	ds_read2_b32 v[8:9], v19 offset0:16 offset1:24
	ds_read2_b32 v[10:11], v19 offset0:49 offset1:57
	ds_read2_b32 v[12:13], v19 offset0:82 offset1:90
	ds_read2_b32 v[26:27], v19 offset0:115 offset1:123
	ds_read2_b32 v[28:29], v19 offset0:148 offset1:156
	ds_read2_b32 v[30:31], v19 offset0:181 offset1:189
	ds_read2_b32 v[32:33], v19 offset0:214 offset1:222
	ds_read2_b32 v[34:35], v19 offset0:247 offset1:255
	v_lshlrev_b32_e32 v0, 12, v0
	v_lshl_add_u64 v[36:37], v[6:7], 0, v[0:1]
	v_or_b32_e32 v0, s0, v39
	v_lshlrev_b32_e32 v0, 12, v0
	s_waitcnt lgkmcnt(6)
	v_cvt_pk_bf16_f32 v2, v8, v10
	s_waitcnt lgkmcnt(4)
	v_cvt_pk_bf16_f32 v3, v12, v26
	s_waitcnt lgkmcnt(2)
	v_cvt_pk_bf16_f32 v4, v28, v30
	s_waitcnt lgkmcnt(0)
	v_cvt_pk_bf16_f32 v5, v32, v34
	v_lshl_add_u64 v[6:7], v[6:7], 0, v[0:1]
	global_store_dwordx4 v[36:37], v[2:5], off sc1
	s_nop 1
	v_cvt_pk_bf16_f32 v2, v9, v11
	v_cvt_pk_bf16_f32 v3, v13, v27
	v_cvt_pk_bf16_f32 v4, v29, v31
	v_cvt_pk_bf16_f32 v5, v33, v35
	global_store_dwordx4 v[6:7], v[2:5], off sc1
	s_waitcnt lgkmcnt(0)
